# gMLP unit loop hand-written: per-WG constants hoisted, next-unit prefetch, 16-byte u/gate/out accesses via channel permutation of MFMA tiles
# speedup vs baseline: 1.0099x; 1.0099x over previous
.LBB0_784:
	s_cmpk_gt_i32 s97, 0x3ff
	s_cbranch_scc1 .LBB0_800
	s_waitcnt lgkmcnt(0)
	v_and_b32_e32 v1, 15, v0
	v_bfe_u32 v2, v0, 4, 2
	v_readfirstlane_b32 s4, v0
	s_and_b32 s5, s97, 7
	v_mov_b32_e32 v11, 0x358637bd
	v_and_b32_e32 v110, 0x7f, v0
	v_lshrrev_b32_e32 v111, 7, v0
	s_lshr_b32 s4, s4, 6
	v_lshl_add_u32 v3, s4, 4, v1
	s_lshr_b32 s28, s4, 1
	s_lshl_b32 s26, s5, 8
	s_add_u32 s20, s92, 0xe400000
	s_addc_u32 s21, s93, 0
	s_add_u32 s20, s20, s26
	s_addc_u32 s21, s21, 0
	s_add_u32 s22, s92, 0x6400800
	s_addc_u32 s23, s93, 0
	s_add_u32 s22, s22, s26
	s_addc_u32 s23, s23, 0
	s_add_u32 s24, s92, 0x1cc10000
	s_addc_u32 s25, s93, 0
	v_mul_u32_u24_e32 v4, 0x2a00, v110
	v_lshl_add_u32 v4, v111, 4, v4
	v_lshlrev_b32_e32 v5, 2, v110
	v_mul_u32_u24_e32 v6, 0x880, v111
	v_lshl_add_u32 v6, v110, 1, v6
	v_mul_u32_u24_e32 v7, 0x2a00, v3
	v_lshl_add_u32 v7, v2, 4, v7
	v_lshlrev_b32_e32 v8, 12, v3
	v_lshl_add_u32 v8, v2, 4, v8
	v_lshrrev_b32_e32 v9, 2, v1
	v_and_b32_e32 v229, 3, v1
	v_lshl_add_u32 v9, v9, 3, v229
	v_mul_u32_u24_e32 v9, 0x110, v9
	v_lshl_add_u32 v9, v2, 4, v9
	s_lshl_b32 s26, s5, 16
	s_add_u32 s6, s84, s26
	s_addc_u32 s7, s85, 0
	v_lshlrev_b32_e32 v224, 9, v3
	v_lshl_add_u32 v224, v2, 5, v224
	global_load_dwordx4 v[60:63], v224, s[6:7] offset:0
	global_load_dwordx4 v[64:67], v224, s[6:7] offset:16
	global_load_dwordx4 v[68:71], v224, s[6:7] offset:128
	global_load_dwordx4 v[72:75], v224, s[6:7] offset:144
	global_load_dwordx4 v[76:79], v224, s[6:7] offset:256
	global_load_dwordx4 v[80:83], v224, s[6:7] offset:272
	global_load_dwordx4 v[84:87], v224, s[6:7] offset:384
	global_load_dwordx4 v[88:91], v224, s[6:7] offset:400
	s_lshl_b32 s26, s5, 9
	s_add_u32 s30, s82, s26
	s_addc_u32 s31, s83, 0
	v_lshlrev_b32_e32 v225, 5, v111
	global_load_dwordx4 v[28:31], v225, s[30:31] offset:0
	global_load_dwordx4 v[32:35], v225, s[30:31] offset:16
	global_load_dwordx4 v[36:39], v225, s[30:31] offset:128
	global_load_dwordx4 v[40:43], v225, s[30:31] offset:144
	global_load_dwordx4 v[44:47], v225, s[30:31] offset:256
	global_load_dwordx4 v[48:51], v225, s[30:31] offset:272
	global_load_dwordx4 v[52:55], v225, s[30:31] offset:384
	global_load_dwordx4 v[56:59], v225, s[30:31] offset:400
	s_add_u32 s32, s86, s26
	s_addc_u32 s33, s87, 0
	v_lshlrev_b32_e32 v226, 2, v3
	global_load_dword v10, v226, s[32:33]
	s_mov_b32 s8, s97
	s_lshr_b32 s9, s8, 3
	s_mul_i32 s27, s9, 0x150000
	s_add_u32 s14, s20, s27
	s_addc_u32 s15, s21, 0
	s_add_u32 s14, s14, 0x1200
	s_addc_u32 s15, s15, 0
	s_add_u32 s10, s14, 0x800
	s_addc_u32 s11, s15, 0
	s_add_u32 s16, s14, 0x1000
	s_addc_u32 s17, s15, 0
	s_lshl_b32 s27, s9, 9
	s_add_u32 s12, s24, s27
	s_addc_u32 s13, s25, 0
	global_load_dwordx4 v[92:95], v4, s[10:11]
	global_load_dwordx4 v[96:99], v4, s[10:11] offset:64
	global_load_dwordx4 v[100:103], v4, s[10:11] offset:128
	global_load_dwordx4 v[104:107], v4, s[10:11] offset:192
	global_load_dword v108, v5, s[12:13]
	global_load_dwordx4 v[128:131], v7, s[14:15]
	global_load_dwordx4 v[132:135], v7, s[14:15] offset:64
	global_load_dwordx4 v[136:139], v7, s[14:15] offset:128
	global_load_dwordx4 v[140:143], v7, s[14:15] offset:192
	global_load_dwordx4 v[144:147], v7, s[16:17]
	global_load_dwordx4 v[148:151], v7, s[16:17] offset:64
	global_load_dwordx4 v[152:155], v7, s[16:17] offset:128
	global_load_dwordx4 v[156:159], v7, s[16:17] offset:192
	s_lshr_b32 s9, s8, 3
	s_lshl_b32 s27, s9, 19
	s_add_u32 s18, s22, s27
	s_addc_u32 s19, s23, 0
	s_waitcnt vmcnt(0)
	v_lshlrev_b32_e32 v227, 3, v2
	v_add_u32_e32 v228, 0, v227
	v_cmp_gt_u32_e32 vcc, v228, v3
	s_nop 1
	v_cndmask_b32_e64 v60, v60, 0, vcc
	v_add_u32_e32 v228, 1, v227
	v_cmp_gt_u32_e32 vcc, v228, v3
	s_nop 1
	v_cndmask_b32_e64 v61, v61, 0, vcc
	v_add_u32_e32 v228, 2, v227
	v_cmp_gt_u32_e32 vcc, v228, v3
	s_nop 1
	v_cndmask_b32_e64 v62, v62, 0, vcc
	v_add_u32_e32 v228, 3, v227
	v_cmp_gt_u32_e32 vcc, v228, v3
	s_nop 1
	v_cndmask_b32_e64 v63, v63, 0, vcc
	v_add_u32_e32 v228, 4, v227
	v_cmp_gt_u32_e32 vcc, v228, v3
	s_nop 1
	v_cndmask_b32_e64 v64, v64, 0, vcc
	v_add_u32_e32 v228, 5, v227
	v_cmp_gt_u32_e32 vcc, v228, v3
	s_nop 1
	v_cndmask_b32_e64 v65, v65, 0, vcc
	v_add_u32_e32 v228, 6, v227
	v_cmp_gt_u32_e32 vcc, v228, v3
	s_nop 1
	v_cndmask_b32_e64 v66, v66, 0, vcc
	v_add_u32_e32 v228, 7, v227
	v_cmp_gt_u32_e32 vcc, v228, v3
	s_nop 1
	v_cndmask_b32_e64 v67, v67, 0, vcc
	v_add_u32_e32 v228, 32, v227
	v_cmp_gt_u32_e32 vcc, v228, v3
	s_nop 1
	v_cndmask_b32_e64 v68, v68, 0, vcc
	v_add_u32_e32 v228, 33, v227
	v_cmp_gt_u32_e32 vcc, v228, v3
	s_nop 1
	v_cndmask_b32_e64 v69, v69, 0, vcc
	v_add_u32_e32 v228, 34, v227
	v_cmp_gt_u32_e32 vcc, v228, v3
	s_nop 1
	v_cndmask_b32_e64 v70, v70, 0, vcc
	v_add_u32_e32 v228, 35, v227
	v_cmp_gt_u32_e32 vcc, v228, v3
	s_nop 1
	v_cndmask_b32_e64 v71, v71, 0, vcc
	v_add_u32_e32 v228, 36, v227
	v_cmp_gt_u32_e32 vcc, v228, v3
	s_nop 1
	v_cndmask_b32_e64 v72, v72, 0, vcc
	v_add_u32_e32 v228, 37, v227
	v_cmp_gt_u32_e32 vcc, v228, v3
	s_nop 1
	v_cndmask_b32_e64 v73, v73, 0, vcc
	v_add_u32_e32 v228, 38, v227
	v_cmp_gt_u32_e32 vcc, v228, v3
	s_nop 1
	v_cndmask_b32_e64 v74, v74, 0, vcc
	v_add_u32_e32 v228, 39, v227
	v_cmp_gt_u32_e32 vcc, v228, v3
	s_nop 1
	v_cndmask_b32_e64 v75, v75, 0, vcc
	v_add_u32_e32 v228, 64, v227
	v_cmp_gt_u32_e32 vcc, v228, v3
	s_nop 1
	v_cndmask_b32_e64 v76, v76, 0, vcc
	v_add_u32_e32 v228, 65, v227
	v_cmp_gt_u32_e32 vcc, v228, v3
	s_nop 1
	v_cndmask_b32_e64 v77, v77, 0, vcc
	v_add_u32_e32 v228, 66, v227
	v_cmp_gt_u32_e32 vcc, v228, v3
	s_nop 1
	v_cndmask_b32_e64 v78, v78, 0, vcc
	v_add_u32_e32 v228, 67, v227
	v_cmp_gt_u32_e32 vcc, v228, v3
	s_nop 1
	v_cndmask_b32_e64 v79, v79, 0, vcc
	v_add_u32_e32 v228, 68, v227
	v_cmp_gt_u32_e32 vcc, v228, v3
	s_nop 1
	v_cndmask_b32_e64 v80, v80, 0, vcc
	v_add_u32_e32 v228, 69, v227
	v_cmp_gt_u32_e32 vcc, v228, v3
	s_nop 1
	v_cndmask_b32_e64 v81, v81, 0, vcc
	v_add_u32_e32 v228, 70, v227
	v_cmp_gt_u32_e32 vcc, v228, v3
	s_nop 1
	v_cndmask_b32_e64 v82, v82, 0, vcc
	v_add_u32_e32 v228, 71, v227
	v_cmp_gt_u32_e32 vcc, v228, v3
	s_nop 1
	v_cndmask_b32_e64 v83, v83, 0, vcc
	v_add_u32_e32 v228, 96, v227
	v_cmp_gt_u32_e32 vcc, v228, v3
	s_nop 1
	v_cndmask_b32_e64 v84, v84, 0, vcc
	v_add_u32_e32 v228, 97, v227
	v_cmp_gt_u32_e32 vcc, v228, v3
	s_nop 1
	v_cndmask_b32_e64 v85, v85, 0, vcc
	v_add_u32_e32 v228, 98, v227
	v_cmp_gt_u32_e32 vcc, v228, v3
	s_nop 1
	v_cndmask_b32_e64 v86, v86, 0, vcc
	v_add_u32_e32 v228, 99, v227
	v_cmp_gt_u32_e32 vcc, v228, v3
	s_nop 1
	v_cndmask_b32_e64 v87, v87, 0, vcc
	v_add_u32_e32 v228, 100, v227
	v_cmp_gt_u32_e32 vcc, v228, v3
	s_nop 1
	v_cndmask_b32_e64 v88, v88, 0, vcc
	v_add_u32_e32 v228, 101, v227
	v_cmp_gt_u32_e32 vcc, v228, v3
	s_nop 1
	v_cndmask_b32_e64 v89, v89, 0, vcc
	v_add_u32_e32 v228, 102, v227
	v_cmp_gt_u32_e32 vcc, v228, v3
	s_nop 1
	v_cndmask_b32_e64 v90, v90, 0, vcc
	v_add_u32_e32 v228, 103, v227
	v_cmp_gt_u32_e32 vcc, v228, v3
	s_nop 1
	v_cndmask_b32_e64 v91, v91, 0, vcc
	v_cvt_pk_bf16_f32 v12, v60, v61
	v_cvt_pk_bf16_f32 v13, v62, v63
	v_cvt_pk_bf16_f32 v14, v64, v65
	v_cvt_pk_bf16_f32 v15, v66, v67
	v_cvt_pk_bf16_f32 v16, v68, v69
	v_cvt_pk_bf16_f32 v17, v70, v71
	v_cvt_pk_bf16_f32 v18, v72, v73
	v_cvt_pk_bf16_f32 v19, v74, v75
	v_cvt_pk_bf16_f32 v20, v76, v77
	v_cvt_pk_bf16_f32 v21, v78, v79
	v_cvt_pk_bf16_f32 v22, v80, v81
	v_cvt_pk_bf16_f32 v23, v82, v83
	v_cvt_pk_bf16_f32 v24, v84, v85
	v_cvt_pk_bf16_f32 v25, v86, v87
	v_cvt_pk_bf16_f32 v26, v88, v89
	v_cvt_pk_bf16_f32 v27, v90, v91
.Lgm_loop:
	v_fmamk_f32 v108, v108, 0x3a800000, v11
	v_rsq_f32_e32 v108, v108
	s_nop 0
	v_lshlrev_b32_e32 v230, 16, v92
	v_and_b32_e32 v231, 0xffff0000, v92
	v_mul_f32_e32 v230, v230, v108
	v_mul_f32_e32 v231, v231, v108
	v_mul_f32_e32 v230, v230, v28
	v_mul_f32_e32 v231, v231, v29
	v_cvt_pk_bf16_f32 v230, v230, v231
	ds_write_b16 v6, v230
	ds_write_b16_d16_hi v6, v230 offset:272
	v_lshlrev_b32_e32 v232, 16, v93
	v_and_b32_e32 v233, 0xffff0000, v93
	v_mul_f32_e32 v232, v232, v108
	v_mul_f32_e32 v233, v233, v108
	v_mul_f32_e32 v232, v232, v30
	v_mul_f32_e32 v233, v233, v31
	v_cvt_pk_bf16_f32 v232, v232, v233
	ds_write_b16 v6, v232 offset:544
	ds_write_b16_d16_hi v6, v232 offset:816
	v_lshlrev_b32_e32 v230, 16, v94
	v_and_b32_e32 v231, 0xffff0000, v94
	v_mul_f32_e32 v230, v230, v108
	v_mul_f32_e32 v231, v231, v108
	v_mul_f32_e32 v230, v230, v32
	v_mul_f32_e32 v231, v231, v33
	v_cvt_pk_bf16_f32 v230, v230, v231
	ds_write_b16 v6, v230 offset:1088
	ds_write_b16_d16_hi v6, v230 offset:1360
	v_lshlrev_b32_e32 v232, 16, v95
	v_and_b32_e32 v233, 0xffff0000, v95
	v_mul_f32_e32 v232, v232, v108
	v_mul_f32_e32 v233, v233, v108
	v_mul_f32_e32 v232, v232, v34
	v_mul_f32_e32 v233, v233, v35
	v_cvt_pk_bf16_f32 v232, v232, v233
	ds_write_b16 v6, v232 offset:1632
	ds_write_b16_d16_hi v6, v232 offset:1904
	v_lshlrev_b32_e32 v230, 16, v96
	v_and_b32_e32 v231, 0xffff0000, v96
	v_mul_f32_e32 v230, v230, v108
	v_mul_f32_e32 v231, v231, v108
	v_mul_f32_e32 v230, v230, v36
	v_mul_f32_e32 v231, v231, v37
	v_cvt_pk_bf16_f32 v230, v230, v231
	ds_write_b16 v6, v230 offset:8704
	ds_write_b16_d16_hi v6, v230 offset:8976
	v_lshlrev_b32_e32 v232, 16, v97
	v_and_b32_e32 v233, 0xffff0000, v97
	v_mul_f32_e32 v232, v232, v108
	v_mul_f32_e32 v233, v233, v108
	v_mul_f32_e32 v232, v232, v38
	v_mul_f32_e32 v233, v233, v39
	v_cvt_pk_bf16_f32 v232, v232, v233
	ds_write_b16 v6, v232 offset:9248
	ds_write_b16_d16_hi v6, v232 offset:9520
	v_lshlrev_b32_e32 v230, 16, v98
	v_and_b32_e32 v231, 0xffff0000, v98
	v_mul_f32_e32 v230, v230, v108
	v_mul_f32_e32 v231, v231, v108
	v_mul_f32_e32 v230, v230, v40
	v_mul_f32_e32 v231, v231, v41
	v_cvt_pk_bf16_f32 v230, v230, v231
	ds_write_b16 v6, v230 offset:9792
	ds_write_b16_d16_hi v6, v230 offset:10064
	v_lshlrev_b32_e32 v232, 16, v99
	v_and_b32_e32 v233, 0xffff0000, v99
	v_mul_f32_e32 v232, v232, v108
	v_mul_f32_e32 v233, v233, v108
	v_mul_f32_e32 v232, v232, v42
	v_mul_f32_e32 v233, v233, v43
	v_cvt_pk_bf16_f32 v232, v232, v233
	ds_write_b16 v6, v232 offset:10336
	ds_write_b16_d16_hi v6, v232 offset:10608
	v_lshlrev_b32_e32 v230, 16, v100
	v_and_b32_e32 v231, 0xffff0000, v100
	v_mul_f32_e32 v230, v230, v108
	v_mul_f32_e32 v231, v231, v108
	v_mul_f32_e32 v230, v230, v44
	v_mul_f32_e32 v231, v231, v45
	v_cvt_pk_bf16_f32 v230, v230, v231
	ds_write_b16 v6, v230 offset:17408
	ds_write_b16_d16_hi v6, v230 offset:17680
	v_lshlrev_b32_e32 v232, 16, v101
	v_and_b32_e32 v233, 0xffff0000, v101
	v_mul_f32_e32 v232, v232, v108
	v_mul_f32_e32 v233, v233, v108
	v_mul_f32_e32 v232, v232, v46
	v_mul_f32_e32 v233, v233, v47
	v_cvt_pk_bf16_f32 v232, v232, v233
	ds_write_b16 v6, v232 offset:17952
	ds_write_b16_d16_hi v6, v232 offset:18224
	v_lshlrev_b32_e32 v230, 16, v102
	v_and_b32_e32 v231, 0xffff0000, v102
	v_mul_f32_e32 v230, v230, v108
	v_mul_f32_e32 v231, v231, v108
	v_mul_f32_e32 v230, v230, v48
	v_mul_f32_e32 v231, v231, v49
	v_cvt_pk_bf16_f32 v230, v230, v231
	ds_write_b16 v6, v230 offset:18496
	ds_write_b16_d16_hi v6, v230 offset:18768
	v_lshlrev_b32_e32 v232, 16, v103
	v_and_b32_e32 v233, 0xffff0000, v103
	v_mul_f32_e32 v232, v232, v108
	v_mul_f32_e32 v233, v233, v108
	v_mul_f32_e32 v232, v232, v50
	v_mul_f32_e32 v233, v233, v51
	v_cvt_pk_bf16_f32 v232, v232, v233
	ds_write_b16 v6, v232 offset:19040
	ds_write_b16_d16_hi v6, v232 offset:19312
	v_lshlrev_b32_e32 v230, 16, v104
	v_and_b32_e32 v231, 0xffff0000, v104
	v_mul_f32_e32 v230, v230, v108
	v_mul_f32_e32 v231, v231, v108
	v_mul_f32_e32 v230, v230, v52
	v_mul_f32_e32 v231, v231, v53
	v_cvt_pk_bf16_f32 v230, v230, v231
	ds_write_b16 v6, v230 offset:26112
	ds_write_b16_d16_hi v6, v230 offset:26384
	v_lshlrev_b32_e32 v232, 16, v105
	v_and_b32_e32 v233, 0xffff0000, v105
	v_mul_f32_e32 v232, v232, v108
	v_mul_f32_e32 v233, v233, v108
	v_mul_f32_e32 v232, v232, v54
	v_mul_f32_e32 v233, v233, v55
	v_cvt_pk_bf16_f32 v232, v232, v233
	ds_write_b16 v6, v232 offset:26656
	ds_write_b16_d16_hi v6, v232 offset:26928
	v_lshlrev_b32_e32 v230, 16, v106
	v_and_b32_e32 v231, 0xffff0000, v106
	v_mul_f32_e32 v230, v230, v108
	v_mul_f32_e32 v231, v231, v108
	v_mul_f32_e32 v230, v230, v56
	v_mul_f32_e32 v231, v231, v57
	v_cvt_pk_bf16_f32 v230, v230, v231
	ds_write_b16 v6, v230 offset:27200
	ds_write_b16_d16_hi v6, v230 offset:27472
	v_lshlrev_b32_e32 v232, 16, v107
	v_and_b32_e32 v233, 0xffff0000, v107
	v_mul_f32_e32 v232, v232, v108
	v_mul_f32_e32 v233, v233, v108
	v_mul_f32_e32 v232, v232, v58
	v_mul_f32_e32 v233, v233, v59
	v_cvt_pk_bf16_f32 v232, v232, v233
	ds_write_b16 v6, v232 offset:27744
	ds_write_b16_d16_hi v6, v232 offset:28016
	s_add_i32 s27, s8, s96
	s_cmpk_lt_i32 s27, 0x400
	s_cselect_b32 s29, s27, s8
	s_lshr_b32 s9, s29, 3
	s_mul_i32 s27, s9, 0x150000
	s_add_u32 s38, s20, s27
	s_addc_u32 s39, s21, 0
	s_add_u32 s38, s38, 0x1200
	s_addc_u32 s39, s39, 0
	s_add_u32 s34, s38, 0x800
	s_addc_u32 s35, s39, 0
	s_add_u32 s40, s38, 0x1000
	s_addc_u32 s41, s39, 0
	s_lshl_b32 s27, s9, 9
	s_add_u32 s36, s24, s27
	s_addc_u32 s37, s25, 0
	global_load_dwordx4 v[112:115], v4, s[34:35]
	global_load_dwordx4 v[116:119], v4, s[34:35] offset:64
	global_load_dwordx4 v[120:123], v4, s[34:35] offset:128
	global_load_dwordx4 v[124:127], v4, s[34:35] offset:192
	global_load_dword v109, v5, s[36:37]
	global_load_dwordx4 v[160:163], v7, s[38:39]
	global_load_dwordx4 v[164:167], v7, s[38:39] offset:64
	global_load_dwordx4 v[168:171], v7, s[38:39] offset:128
	global_load_dwordx4 v[172:175], v7, s[38:39] offset:192
	global_load_dwordx4 v[176:179], v7, s[40:41]
	global_load_dwordx4 v[180:183], v7, s[40:41] offset:64
	global_load_dwordx4 v[184:187], v7, s[40:41] offset:128
	global_load_dwordx4 v[188:191], v7, s[40:41] offset:192
	s_waitcnt lgkmcnt(0)
	s_barrier
	ds_read_b128 v[60:63], v9 offset:0
	ds_read_b128 v[64:67], v9 offset:1088
	ds_read_b128 v[68:71], v9 offset:8704
	ds_read_b128 v[72:75], v9 offset:9792
	ds_read_b128 v[76:79], v9 offset:17408
	ds_read_b128 v[80:83], v9 offset:18496
	ds_read_b128 v[84:87], v9 offset:26112
	ds_read_b128 v[88:91], v9 offset:27200
	s_waitcnt lgkmcnt(7)
	v_mfma_f32_16x16x32_bf16 v[192:195], v[60:63], v[12:15], 0
	s_waitcnt lgkmcnt(6)
	v_mfma_f32_16x16x32_bf16 v[196:199], v[64:67], v[12:15], 0
	s_waitcnt lgkmcnt(5)
	v_mfma_f32_16x16x32_bf16 v[200:203], v[68:71], v[12:15], 0
	s_waitcnt lgkmcnt(4)
	v_mfma_f32_16x16x32_bf16 v[204:207], v[72:75], v[12:15], 0
	s_waitcnt lgkmcnt(3)
	v_mfma_f32_16x16x32_bf16 v[208:211], v[76:79], v[12:15], 0
	s_waitcnt lgkmcnt(2)
	v_mfma_f32_16x16x32_bf16 v[212:215], v[80:83], v[12:15], 0
	s_waitcnt lgkmcnt(1)
	v_mfma_f32_16x16x32_bf16 v[216:219], v[84:87], v[12:15], 0
	s_waitcnt lgkmcnt(0)
	v_mfma_f32_16x16x32_bf16 v[220:223], v[88:91], v[12:15], 0
	s_cmp_lt_u32 s28, 1
	s_cbranch_scc1 .Lgm_mdone
	ds_read_b128 v[60:63], v9 offset:64
	ds_read_b128 v[64:67], v9 offset:1152
	ds_read_b128 v[68:71], v9 offset:8768
	ds_read_b128 v[72:75], v9 offset:9856
	ds_read_b128 v[76:79], v9 offset:17472
	ds_read_b128 v[80:83], v9 offset:18560
	ds_read_b128 v[84:87], v9 offset:26176
	ds_read_b128 v[88:91], v9 offset:27264
	s_waitcnt lgkmcnt(7)
	v_mfma_f32_16x16x32_bf16 v[192:195], v[60:63], v[16:19], v[192:195]
	s_waitcnt lgkmcnt(6)
	v_mfma_f32_16x16x32_bf16 v[196:199], v[64:67], v[16:19], v[196:199]
	s_waitcnt lgkmcnt(5)
	v_mfma_f32_16x16x32_bf16 v[200:203], v[68:71], v[16:19], v[200:203]
	s_waitcnt lgkmcnt(4)
	v_mfma_f32_16x16x32_bf16 v[204:207], v[72:75], v[16:19], v[204:207]
	s_waitcnt lgkmcnt(3)
	v_mfma_f32_16x16x32_bf16 v[208:211], v[76:79], v[16:19], v[208:211]
	s_waitcnt lgkmcnt(2)
	v_mfma_f32_16x16x32_bf16 v[212:215], v[80:83], v[16:19], v[212:215]
	s_waitcnt lgkmcnt(1)
	v_mfma_f32_16x16x32_bf16 v[216:219], v[84:87], v[16:19], v[216:219]
	s_waitcnt lgkmcnt(0)
	v_mfma_f32_16x16x32_bf16 v[220:223], v[88:91], v[16:19], v[220:223]
	s_cmp_lt_u32 s28, 2
	s_cbranch_scc1 .Lgm_mdone
	ds_read_b128 v[60:63], v9 offset:128
	ds_read_b128 v[64:67], v9 offset:1216
	ds_read_b128 v[68:71], v9 offset:8832
	ds_read_b128 v[72:75], v9 offset:9920
	ds_read_b128 v[76:79], v9 offset:17536
	ds_read_b128 v[80:83], v9 offset:18624
	ds_read_b128 v[84:87], v9 offset:26240
	ds_read_b128 v[88:91], v9 offset:27328
	s_waitcnt lgkmcnt(7)
	v_mfma_f32_16x16x32_bf16 v[192:195], v[60:63], v[20:23], v[192:195]
	s_waitcnt lgkmcnt(6)
	v_mfma_f32_16x16x32_bf16 v[196:199], v[64:67], v[20:23], v[196:199]
	s_waitcnt lgkmcnt(5)
	v_mfma_f32_16x16x32_bf16 v[200:203], v[68:71], v[20:23], v[200:203]
	s_waitcnt lgkmcnt(4)
	v_mfma_f32_16x16x32_bf16 v[204:207], v[72:75], v[20:23], v[204:207]
	s_waitcnt lgkmcnt(3)
	v_mfma_f32_16x16x32_bf16 v[208:211], v[76:79], v[20:23], v[208:211]
	s_waitcnt lgkmcnt(2)
	v_mfma_f32_16x16x32_bf16 v[212:215], v[80:83], v[20:23], v[212:215]
	s_waitcnt lgkmcnt(1)
	v_mfma_f32_16x16x32_bf16 v[216:219], v[84:87], v[20:23], v[216:219]
	s_waitcnt lgkmcnt(0)
	v_mfma_f32_16x16x32_bf16 v[220:223], v[88:91], v[20:23], v[220:223]
	s_cmp_lt_u32 s28, 3
	s_cbranch_scc1 .Lgm_mdone
	ds_read_b128 v[60:63], v9 offset:192
	ds_read_b128 v[64:67], v9 offset:1280
	ds_read_b128 v[68:71], v9 offset:8896
	ds_read_b128 v[72:75], v9 offset:9984
	ds_read_b128 v[76:79], v9 offset:17600
	ds_read_b128 v[80:83], v9 offset:18688
	ds_read_b128 v[84:87], v9 offset:26304
	ds_read_b128 v[88:91], v9 offset:27392
	s_waitcnt lgkmcnt(7)
	v_mfma_f32_16x16x32_bf16 v[192:195], v[60:63], v[24:27], v[192:195]
	s_waitcnt lgkmcnt(6)
	v_mfma_f32_16x16x32_bf16 v[196:199], v[64:67], v[24:27], v[196:199]
	s_waitcnt lgkmcnt(5)
	v_mfma_f32_16x16x32_bf16 v[200:203], v[68:71], v[24:27], v[200:203]
	s_waitcnt lgkmcnt(4)
	v_mfma_f32_16x16x32_bf16 v[204:207], v[72:75], v[24:27], v[204:207]
	s_waitcnt lgkmcnt(3)
	v_mfma_f32_16x16x32_bf16 v[208:211], v[76:79], v[24:27], v[208:211]
	s_waitcnt lgkmcnt(2)
	v_mfma_f32_16x16x32_bf16 v[212:215], v[80:83], v[24:27], v[212:215]
	s_waitcnt lgkmcnt(1)
	v_mfma_f32_16x16x32_bf16 v[216:219], v[84:87], v[24:27], v[216:219]
	s_waitcnt lgkmcnt(0)
	v_mfma_f32_16x16x32_bf16 v[220:223], v[88:91], v[24:27], v[220:223]
.Lgm_mdone:
	s_waitcnt lgkmcnt(0)
	s_barrier
	s_nop 7
	v_lshlrev_b32_e32 v224, 16, v128
	v_and_b32_e32 v225, 0xffff0000, v128
	v_lshlrev_b32_e32 v226, 16, v129
	v_and_b32_e32 v227, 0xffff0000, v129
	v_lshlrev_b32_e32 v228, 16, v144
	v_and_b32_e32 v229, 0xffff0000, v144
	v_lshlrev_b32_e32 v230, 16, v145
	v_and_b32_e32 v231, 0xffff0000, v145
	v_add_f32_e32 v192, v192, v10
	v_add_f32_e32 v193, v193, v10
	v_add_f32_e32 v194, v194, v10
	v_add_f32_e32 v195, v195, v10
	v_mul_f32_e32 v192, v224, v192
	v_mul_f32_e32 v193, v225, v193
	v_mul_f32_e32 v194, v226, v194
	v_mul_f32_e32 v195, v227, v195
	v_mul_f32_e32 v192, v192, v228
	v_mul_f32_e32 v193, v193, v229
	v_mul_f32_e32 v194, v194, v230
	v_mul_f32_e32 v195, v195, v231
	v_lshlrev_b32_e32 v224, 16, v130
	v_and_b32_e32 v225, 0xffff0000, v130
	v_lshlrev_b32_e32 v226, 16, v131
	v_and_b32_e32 v227, 0xffff0000, v131
	v_lshlrev_b32_e32 v228, 16, v146
	v_and_b32_e32 v229, 0xffff0000, v146
	v_lshlrev_b32_e32 v230, 16, v147
	v_and_b32_e32 v231, 0xffff0000, v147
	v_add_f32_e32 v196, v196, v10
	v_add_f32_e32 v197, v197, v10
	v_add_f32_e32 v198, v198, v10
	v_add_f32_e32 v199, v199, v10
	v_mul_f32_e32 v196, v224, v196
	v_mul_f32_e32 v197, v225, v197
	v_mul_f32_e32 v198, v226, v198
	v_mul_f32_e32 v199, v227, v199
	v_mul_f32_e32 v196, v196, v228
	v_mul_f32_e32 v197, v197, v229
	v_mul_f32_e32 v198, v198, v230
	v_mul_f32_e32 v199, v199, v231
	v_cvt_pk_bf16_f32 v192, v192, v193
	v_cvt_pk_bf16_f32 v193, v194, v195
	v_cvt_pk_bf16_f32 v194, v196, v197
	v_cvt_pk_bf16_f32 v195, v198, v199
	global_store_dwordx4 v8, v[192:195], s[18:19]
	v_lshlrev_b32_e32 v224, 16, v132
	v_and_b32_e32 v225, 0xffff0000, v132
	v_lshlrev_b32_e32 v226, 16, v133
	v_and_b32_e32 v227, 0xffff0000, v133
	v_lshlrev_b32_e32 v228, 16, v148
	v_and_b32_e32 v229, 0xffff0000, v148
	v_lshlrev_b32_e32 v230, 16, v149
	v_and_b32_e32 v231, 0xffff0000, v149
	v_add_f32_e32 v200, v200, v10
	v_add_f32_e32 v201, v201, v10
	v_add_f32_e32 v202, v202, v10
	v_add_f32_e32 v203, v203, v10
	v_mul_f32_e32 v200, v224, v200
	v_mul_f32_e32 v201, v225, v201
	v_mul_f32_e32 v202, v226, v202
	v_mul_f32_e32 v203, v227, v203
	v_mul_f32_e32 v200, v200, v228
	v_mul_f32_e32 v201, v201, v229
	v_mul_f32_e32 v202, v202, v230
	v_mul_f32_e32 v203, v203, v231
	v_lshlrev_b32_e32 v224, 16, v134
	v_and_b32_e32 v225, 0xffff0000, v134
	v_lshlrev_b32_e32 v226, 16, v135
	v_and_b32_e32 v227, 0xffff0000, v135
	v_lshlrev_b32_e32 v228, 16, v150
	v_and_b32_e32 v229, 0xffff0000, v150
	v_lshlrev_b32_e32 v230, 16, v151
	v_and_b32_e32 v231, 0xffff0000, v151
	v_add_f32_e32 v204, v204, v10
	v_add_f32_e32 v205, v205, v10
	v_add_f32_e32 v206, v206, v10
	v_add_f32_e32 v207, v207, v10
	v_mul_f32_e32 v204, v224, v204
	v_mul_f32_e32 v205, v225, v205
	v_mul_f32_e32 v206, v226, v206
	v_mul_f32_e32 v207, v227, v207
	v_mul_f32_e32 v204, v204, v228
	v_mul_f32_e32 v205, v205, v229
	v_mul_f32_e32 v206, v206, v230
	v_mul_f32_e32 v207, v207, v231
	v_cvt_pk_bf16_f32 v200, v200, v201
	v_cvt_pk_bf16_f32 v201, v202, v203
	v_cvt_pk_bf16_f32 v202, v204, v205
	v_cvt_pk_bf16_f32 v203, v206, v207
	global_store_dwordx4 v8, v[200:203], s[18:19] offset:64
	v_lshlrev_b32_e32 v224, 16, v136
	v_and_b32_e32 v225, 0xffff0000, v136
	v_lshlrev_b32_e32 v226, 16, v137
	v_and_b32_e32 v227, 0xffff0000, v137
	v_lshlrev_b32_e32 v228, 16, v152
	v_and_b32_e32 v229, 0xffff0000, v152
	v_lshlrev_b32_e32 v230, 16, v153
	v_and_b32_e32 v231, 0xffff0000, v153
	v_add_f32_e32 v208, v208, v10
	v_add_f32_e32 v209, v209, v10
	v_add_f32_e32 v210, v210, v10
	v_add_f32_e32 v211, v211, v10
	v_mul_f32_e32 v208, v224, v208
	v_mul_f32_e32 v209, v225, v209
	v_mul_f32_e32 v210, v226, v210
	v_mul_f32_e32 v211, v227, v211
	v_mul_f32_e32 v208, v208, v228
	v_mul_f32_e32 v209, v209, v229
	v_mul_f32_e32 v210, v210, v230
	v_mul_f32_e32 v211, v211, v231
	v_lshlrev_b32_e32 v224, 16, v138
	v_and_b32_e32 v225, 0xffff0000, v138
	v_lshlrev_b32_e32 v226, 16, v139
	v_and_b32_e32 v227, 0xffff0000, v139
	v_lshlrev_b32_e32 v228, 16, v154
	v_and_b32_e32 v229, 0xffff0000, v154
	v_lshlrev_b32_e32 v230, 16, v155
	v_and_b32_e32 v231, 0xffff0000, v155
	v_add_f32_e32 v212, v212, v10
	v_add_f32_e32 v213, v213, v10
	v_add_f32_e32 v214, v214, v10
	v_add_f32_e32 v215, v215, v10
	v_mul_f32_e32 v212, v224, v212
	v_mul_f32_e32 v213, v225, v213
	v_mul_f32_e32 v214, v226, v214
	v_mul_f32_e32 v215, v227, v215
	v_mul_f32_e32 v212, v212, v228
	v_mul_f32_e32 v213, v213, v229
	v_mul_f32_e32 v214, v214, v230
	v_mul_f32_e32 v215, v215, v231
	v_cvt_pk_bf16_f32 v208, v208, v209
	v_cvt_pk_bf16_f32 v209, v210, v211
	v_cvt_pk_bf16_f32 v210, v212, v213
	v_cvt_pk_bf16_f32 v211, v214, v215
	global_store_dwordx4 v8, v[208:211], s[18:19] offset:128
	v_lshlrev_b32_e32 v224, 16, v140
	v_and_b32_e32 v225, 0xffff0000, v140
	v_lshlrev_b32_e32 v226, 16, v141
	v_and_b32_e32 v227, 0xffff0000, v141
	v_lshlrev_b32_e32 v228, 16, v156
	v_and_b32_e32 v229, 0xffff0000, v156
	v_lshlrev_b32_e32 v230, 16, v157
	v_and_b32_e32 v231, 0xffff0000, v157
	v_add_f32_e32 v216, v216, v10
	v_add_f32_e32 v217, v217, v10
	v_add_f32_e32 v218, v218, v10
	v_add_f32_e32 v219, v219, v10
	v_mul_f32_e32 v216, v224, v216
	v_mul_f32_e32 v217, v225, v217
	v_mul_f32_e32 v218, v226, v218
	v_mul_f32_e32 v219, v227, v219
	v_mul_f32_e32 v216, v216, v228
	v_mul_f32_e32 v217, v217, v229
	v_mul_f32_e32 v218, v218, v230
	v_mul_f32_e32 v219, v219, v231
	v_lshlrev_b32_e32 v224, 16, v142
	v_and_b32_e32 v225, 0xffff0000, v142
	v_lshlrev_b32_e32 v226, 16, v143
	v_and_b32_e32 v227, 0xffff0000, v143
	v_lshlrev_b32_e32 v228, 16, v158
	v_and_b32_e32 v229, 0xffff0000, v158
	v_lshlrev_b32_e32 v230, 16, v159
	v_and_b32_e32 v231, 0xffff0000, v159
	v_add_f32_e32 v220, v220, v10
	v_add_f32_e32 v221, v221, v10
	v_add_f32_e32 v222, v222, v10
	v_add_f32_e32 v223, v223, v10
	v_mul_f32_e32 v220, v224, v220
	v_mul_f32_e32 v221, v225, v221
	v_mul_f32_e32 v222, v226, v222
	v_mul_f32_e32 v223, v227, v223
	v_mul_f32_e32 v220, v220, v228
	v_mul_f32_e32 v221, v221, v229
	v_mul_f32_e32 v222, v222, v230
	v_mul_f32_e32 v223, v223, v231
	v_cvt_pk_bf16_f32 v216, v216, v217
	v_cvt_pk_bf16_f32 v217, v218, v219
	v_cvt_pk_bf16_f32 v218, v220, v221
	v_cvt_pk_bf16_f32 v219, v222, v223
	global_store_dwordx4 v8, v[216:219], s[18:19] offset:192
	s_waitcnt vmcnt(4)
	v_mov_b32_e32 v92, v112
	v_mov_b32_e32 v93, v113
	v_mov_b32_e32 v94, v114
	v_mov_b32_e32 v95, v115
	v_mov_b32_e32 v96, v116
	v_mov_b32_e32 v97, v117
	v_mov_b32_e32 v98, v118
	v_mov_b32_e32 v99, v119
	v_mov_b32_e32 v100, v120
	v_mov_b32_e32 v101, v121
	v_mov_b32_e32 v102, v122
	v_mov_b32_e32 v103, v123
	v_mov_b32_e32 v104, v124
	v_mov_b32_e32 v105, v125
	v_mov_b32_e32 v106, v126
	v_mov_b32_e32 v107, v127
	v_mov_b32_e32 v108, v109
	v_mov_b32_e32 v128, v160
	v_mov_b32_e32 v129, v161
	v_mov_b32_e32 v130, v162
	v_mov_b32_e32 v131, v163
	v_mov_b32_e32 v132, v164
	v_mov_b32_e32 v133, v165
	v_mov_b32_e32 v134, v166
	v_mov_b32_e32 v135, v167
	v_mov_b32_e32 v136, v168
	v_mov_b32_e32 v137, v169
	v_mov_b32_e32 v138, v170
	v_mov_b32_e32 v139, v171
	v_mov_b32_e32 v140, v172
	v_mov_b32_e32 v141, v173
	v_mov_b32_e32 v142, v174
	v_mov_b32_e32 v143, v175
	v_mov_b32_e32 v144, v176
	v_mov_b32_e32 v145, v177
	v_mov_b32_e32 v146, v178
	v_mov_b32_e32 v147, v179
	v_mov_b32_e32 v148, v180
	v_mov_b32_e32 v149, v181
	v_mov_b32_e32 v150, v182
	v_mov_b32_e32 v151, v183
	v_mov_b32_e32 v152, v184
	v_mov_b32_e32 v153, v185
	v_mov_b32_e32 v154, v186
	v_mov_b32_e32 v155, v187
	v_mov_b32_e32 v156, v188
	v_mov_b32_e32 v157, v189
	v_mov_b32_e32 v158, v190
	v_mov_b32_e32 v159, v191
	s_lshr_b32 s9, s29, 3
	s_lshl_b32 s27, s9, 19
	s_add_u32 s18, s22, s27
	s_addc_u32 s19, s23, 0
	s_add_i32 s8, s8, s96
	s_cmpk_lt_i32 s8, 0x400
	s_cbranch_scc1 .Lgm_loop

.LBB0_1212:
	s_or_b64 exec, exec, s[0:1]
	v_and_b32_e32 v38, 0xffff, v30
	v_lshrrev_b32_e32 v30, 16, v30
	v_lshl_or_b32 v38, v34, 16, v38
	v_and_or_b32 v30, v34, s38, v30
	v_add_u32_e32 v34, 0x5000, v95
	ds_write2_b32 v34, v38, v30 offset1:36
	v_and_b32_e32 v30, 0xffff, v31
	v_lshrrev_b32_e32 v31, 16, v31
	v_lshl_or_b32 v30, v35, 16, v30
	v_and_or_b32 v31, v35, s38, v31
	ds_write2_b32 v34, v30, v31 offset0:72 offset1:108
	v_and_b32_e32 v30, 0xffff, v32
	v_lshrrev_b32_e32 v31, 16, v32
	v_lshl_or_b32 v30, v36, 16, v30
	v_and_or_b32 v31, v36, s38, v31
	ds_write2_b32 v34, v30, v31 offset0:144 offset1:180
	v_and_b32_e32 v30, 0xffff, v33
	v_lshrrev_b32_e32 v31, 16, v33
	v_lshl_or_b32 v30, v37, 16, v30
	v_and_or_b32 v31, v37, s38, v31
	ds_write2_b32 v34, v30, v31 offset0:216 offset1:252
	v_and_b32_e32 v30, 0xffff, v22
	v_lshrrev_b32_e32 v22, 16, v22
	v_lshl_or_b32 v30, v26, 16, v30
	v_and_or_b32 v22, v26, s38, v22
	v_add_u32_e32 v26, 0x5000, v96
	ds_write2_b32 v26, v30, v22 offset1:36
	v_and_b32_e32 v22, 0xffff, v23
	v_lshrrev_b32_e32 v23, 16, v23
	v_lshl_or_b32 v22, v27, 16, v22
	v_and_or_b32 v23, v27, s38, v23
	ds_write2_b32 v26, v22, v23 offset0:72 offset1:108
	v_and_b32_e32 v22, 0xffff, v24
	v_lshrrev_b32_e32 v23, 16, v24
	v_lshl_or_b32 v22, v28, 16, v22
	v_and_or_b32 v23, v28, s38, v23
	ds_write2_b32 v26, v22, v23 offset0:144 offset1:180
	v_and_b32_e32 v22, 0xffff, v25
	v_lshrrev_b32_e32 v23, 16, v25
	v_lshl_or_b32 v22, v29, 16, v22
	v_and_or_b32 v23, v29, s38, v23
	ds_write2_b32 v26, v22, v23 offset0:216 offset1:252
	s_waitcnt lgkmcnt(0)
	s_barrier
	ds_read_b128 v[22:25], v97 offset:2048
	ds_read_b128 v[26:29], v98 offset:20480
	ds_read_b128 v[30:33], v97 offset:2112
	ds_read_b128 v[34:37], v98 offset:20544
	ds_read_b128 v[38:41], v98 offset:22784
	ds_read_b128 v[60:63], v98 offset:22848
	ds_read_b128 v[64:67], v98 offset:25088
	ds_read_b128 v[68:71], v98 offset:25152
	ds_read_b128 v[72:75], v98 offset:27392
	ds_read_b128 v[114:117], v98 offset:27456
	ds_read_b128 v[118:121], v98 offset:29696
	ds_read_b128 v[122:125], v98 offset:29760
	ds_read_b128 v[126:129], v98 offset:32000
	ds_read_b128 v[130:133], v98 offset:32064
	ds_read_b128 v[134:137], v98 offset:34304
	ds_read_b128 v[138:141], v98 offset:34368
	ds_read_b128 v[142:145], v98 offset:36608
	ds_read_b128 v[146:149], v98 offset:36672
	s_lshl_b64 s[0:1], s[16:17], 18
	s_waitcnt lgkmcnt(14)
	v_mfma_f32_16x16x32_bf16 v[26:29], v[22:25], v[26:29], 0
	ds_read_b128 v[150:153], v98 offset:38912
	ds_read_b128 v[154:157], v98 offset:38976
	ds_read_b128 v[158:161], v98 offset:41216
	ds_read_b128 v[162:165], v98 offset:41280
	ds_read_b128 v[166:169], v98 offset:43520
	ds_read_b128 v[170:173], v98 offset:43584
	ds_read_b128 v[174:177], v98 offset:45824
	ds_read_b128 v[178:181], v98 offset:45888
	ds_read_b128 v[182:185], v98 offset:48128
	ds_read_b128 v[186:189], v98 offset:48192
	ds_read_b128 v[190:193], v98 offset:50432
	ds_read_b128 v[194:197], v98 offset:50496
	ds_read_b128 v[198:201], v98 offset:52736
	ds_read_b128 v[202:205], v98 offset:52800
	ds_read_b128 v[206:209], v98 offset:55040
	ds_read_b128 v[210:213], v98 offset:55104
	s_add_u32 s16, s23, s0
	s_waitcnt lgkmcnt(14)
	v_mfma_f32_16x16x32_bf16 v[38:41], v[22:25], v[38:41], 0
	s_addc_u32 s17, s24, s1
	s_ashr_i32 s15, s14, 31
	s_lshl_b64 s[0:1], s[14:15], 16
	v_mfma_f32_16x16x32_bf16 v[64:67], v[22:25], v[64:67], 0
	s_add_u32 s0, s16, s0
	s_addc_u32 s1, s17, s1
	v_mov_b32_e32 v57, v43
	v_mfma_f32_16x16x32_bf16 v[72:75], v[22:25], v[72:75], 0
	v_mov_b32_e32 v59, v43
	s_add_i32 s27, s27, s28
	s_add_i32 s29, s29, s30
	v_mfma_f32_16x16x32_bf16 v[134:137], v[22:25], v[134:137], 0
	v_mfma_f32_16x16x32_bf16 v[142:145], v[22:25], v[142:145], 0
	v_mfma_f32_16x16x32_bf16 v[118:121], v[22:25], v[118:121], 0
	v_mfma_f32_16x16x32_bf16 v[126:129], v[22:25], v[126:129], 0
	v_mfma_f32_16x16x32_bf16 v[150:153], v[22:25], v[150:153], 0
	s_waitcnt lgkmcnt(13)
	v_mfma_f32_16x16x32_bf16 v[158:161], v[22:25], v[158:161], 0
	s_waitcnt lgkmcnt(11)
	v_mfma_f32_16x16x32_bf16 v[166:169], v[22:25], v[166:169], 0
	s_waitcnt lgkmcnt(9)
	v_mfma_f32_16x16x32_bf16 v[174:177], v[22:25], v[174:177], 0
	s_waitcnt lgkmcnt(7)
	v_mfma_f32_16x16x32_bf16 v[182:185], v[22:25], v[182:185], 0
	s_waitcnt lgkmcnt(5)
	v_mfma_f32_16x16x32_bf16 v[190:193], v[22:25], v[190:193], 0
	s_waitcnt lgkmcnt(3)
	v_mfma_f32_16x16x32_bf16 v[198:201], v[22:25], v[198:201], 0
	s_waitcnt lgkmcnt(1)
	v_mfma_f32_16x16x32_bf16 v[22:25], v[22:25], v[206:209], 0
	v_mfma_f32_16x16x32_bf16 v[26:29], v[30:33], v[34:37], v[26:29]
	v_mfma_f32_16x16x32_bf16 v[34:37], v[30:33], v[60:63], v[38:41]
	v_mfma_f32_16x16x32_bf16 v[38:41], v[30:33], v[68:71], v[64:67]
	v_mfma_f32_16x16x32_bf16 v[60:63], v[30:33], v[114:117], v[72:75]
	s_nop 5
	v_cvt_pk_bf16_f32 v34, v34, v35
	v_cvt_pk_bf16_f32 v35, v36, v37
	v_mfma_f32_16x16x32_bf16 v[72:75], v[30:33], v[138:141], v[134:137]
	v_lshl_add_u64 v[138:139], s[0:1], 0, v[42:43]
	s_mov_b32 s0, s43
	v_mfma_f32_16x16x32_bf16 v[114:117], v[30:33], v[146:149], v[142:145]
	s_nop 2
	v_lshl_add_u64 v[142:143], v[138:139], 0, v[56:57]
	v_lshl_add_u64 v[142:143], v[142:143], 0, v[58:59]
	v_mfma_f32_16x16x32_bf16 v[64:67], v[30:33], v[122:125], v[118:121]
	v_cvt_pk_bf16_f32 v144, v26, v27
	v_cvt_pk_bf16_f32 v145, v28, v29
	global_store_dwordx2 v[142:143], v[144:145], off
	v_mfma_f32_16x16x32_bf16 v[68:71], v[30:33], v[130:133], v[126:129]
	v_mfma_f32_16x16x32_bf16 v[118:121], v[30:33], v[154:157], v[150:153]
	v_mfma_f32_16x16x32_bf16 v[122:125], v[30:33], v[162:165], v[158:161]
	v_mfma_f32_16x16x32_bf16 v[126:129], v[30:33], v[170:173], v[166:169]
	v_mfma_f32_16x16x32_bf16 v[130:133], v[30:33], v[178:181], v[174:177]
	v_mfma_f32_16x16x32_bf16 v[134:137], v[30:33], v[186:189], v[182:185]
	v_mfma_f32_16x16x32_bf16 v[138:141], v[30:33], v[194:197], v[190:193]
	v_mfma_f32_16x16x32_bf16 v[26:29], v[30:33], v[202:205], v[198:201]
	s_waitcnt lgkmcnt(0)
	v_mfma_f32_16x16x32_bf16 v[22:25], v[30:33], v[210:213], v[22:25]
	v_add_co_u32_e32 v30, vcc, s18, v142
	v_cvt_pk_bf16_f32 v32, v38, v39
	s_nop 0
	v_addc_co_u32_e32 v31, vcc, 0, v143, vcc
	v_cvt_pk_bf16_f32 v33, v40, v41
	global_store_dwordx2 v[30:31], v[32:33], off
	v_add_co_u32_e32 v32, vcc, s19, v142
	global_store_dwordx2 v[30:31], v[34:35], off offset:-4096
	v_cvt_pk_bf16_f32 v30, v60, v61
	v_cvt_pk_bf16_f32 v31, v62, v63
	v_addc_co_u32_e32 v33, vcc, 0, v143, vcc
	global_store_dwordx2 v[32:33], v[30:31], off offset:-4096
	v_cvt_pk_bf16_f32 v30, v64, v65
	v_cvt_pk_bf16_f32 v31, v66, v67
	global_store_dwordx2 v[32:33], v[30:31], off
	v_add_co_u32_e32 v32, vcc, s20, v142
	v_cvt_pk_bf16_f32 v30, v68, v69
	v_cvt_pk_bf16_f32 v31, v70, v71
	v_addc_co_u32_e32 v33, vcc, 0, v143, vcc
	global_store_dwordx2 v[32:33], v[30:31], off offset:-4096
	v_cvt_pk_bf16_f32 v30, v72, v73
	v_cvt_pk_bf16_f32 v31, v74, v75
	global_store_dwordx2 v[32:33], v[30:31], off
	v_add_co_u32_e32 v32, vcc, s39, v142
	v_cvt_pk_bf16_f32 v30, v114, v115
	v_cvt_pk_bf16_f32 v31, v116, v117
	v_addc_co_u32_e32 v33, vcc, 0, v143, vcc
	global_store_dwordx2 v[32:33], v[30:31], off offset:-4096
	v_cvt_pk_bf16_f32 v30, v118, v119
	v_cvt_pk_bf16_f32 v31, v120, v121
	global_store_dwordx2 v[32:33], v[30:31], off
	v_add_co_u32_e32 v32, vcc, s40, v142
	v_cvt_pk_bf16_f32 v30, v122, v123
	v_cvt_pk_bf16_f32 v31, v124, v125
	v_addc_co_u32_e32 v33, vcc, 0, v143, vcc
	global_store_dwordx2 v[32:33], v[30:31], off offset:-4096
	v_cvt_pk_bf16_f32 v30, v126, v127
	v_cvt_pk_bf16_f32 v31, v128, v129
	global_store_dwordx2 v[32:33], v[30:31], off
	v_add_co_u32_e32 v32, vcc, s41, v142
	v_cvt_pk_bf16_f32 v30, v130, v131
	v_cvt_pk_bf16_f32 v31, v132, v133
	v_addc_co_u32_e32 v33, vcc, 0, v143, vcc
	global_store_dwordx2 v[32:33], v[30:31], off offset:-4096
	v_cvt_pk_bf16_f32 v30, v134, v135
	v_cvt_pk_bf16_f32 v31, v136, v137
	global_store_dwordx2 v[32:33], v[30:31], off
	v_add_co_u32_e32 v32, vcc, s42, v142
	v_cvt_pk_bf16_f32 v22, v22, v23
	s_nop 0
	v_addc_co_u32_e32 v33, vcc, 0, v143, vcc
	v_cvt_pk_bf16_f32 v23, v24, v25
	v_add_co_u32_e32 v24, vcc, 0xf000, v142
	v_cvt_pk_bf16_f32 v30, v138, v139
	v_cvt_pk_bf16_f32 v31, v140, v141
	v_cvt_pk_bf16_f32 v26, v26, v27
	v_cvt_pk_bf16_f32 v27, v28, v29
	v_addc_co_u32_e32 v25, vcc, 0, v143, vcc
	global_store_dwordx2 v[32:33], v[30:31], off offset:-4096
	global_store_dwordx2 v[32:33], v[26:27], off
	global_store_dwordx2 v[24:25], v[22:23], off
	s_waitcnt vmcnt(16)
	v_lshlrev_b32_e32 v53, 16, v214
	v_lshlrev_b32_e32 v103, 16, v216
	v_lshlrev_b32_e32 v105, 16, v217
	v_lshlrev_b32_e32 v104, 16, v218
	v_lshlrev_b32_e32 v102, 16, v219
	v_lshlrev_b32_e32 v55, 16, v220
	v_lshlrev_b32_e32 v51, 16, v221
	v_lshlrev_b32_e32 v101, 16, v215
	v_lshlrev_b32_e32 v107, 16, v222
	v_lshlrev_b32_e32 v109, 16, v223
	v_lshlrev_b32_e32 v111, 16, v224
	v_lshlrev_b32_e32 v113, 16, v225
	v_lshlrev_b32_e32 v112, 16, v226
	v_lshlrev_b32_e32 v110, 16, v227
	v_lshlrev_b32_e32 v108, 16, v228
	v_lshlrev_b32_e32 v106, 16, v229
	v_mov_b64_e32 v[32:33], v[4:5]
	v_mov_b64_e32 v[36:37], v[12:13]
	v_mov_b64_e32 v[24:25], v[16:17]
	v_mov_b64_e32 v[28:29], v[20:21]
	v_mov_b64_e32 v[40:41], v[8:9]
	s_andn2_b64 vcc, exec, s[12:13]
	v_mov_b64_e32 v[30:31], v[2:3]
	v_mov_b64_e32 v[34:35], v[10:11]
	v_mov_b64_e32 v[22:23], v[14:15]
	v_mov_b64_e32 v[26:27], v[18:19]
	v_mov_b64_e32 v[38:39], v[6:7]
	v_mov_b32_e32 v68, v51
	v_mov_b32_e32 v69, v53
	v_mov_b32_e32 v70, v55
	v_mov_b32_e32 v71, v101
	v_mov_b32_e32 v74, v102
	v_mov_b32_e32 v75, v103
	v_mov_b32_e32 v72, v104
	v_mov_b32_e32 v73, v105
	v_mov_b32_e32 v60, v106
	v_mov_b32_e32 v61, v107
	v_mov_b32_e32 v62, v108
	v_mov_b32_e32 v63, v109
	v_mov_b32_e32 v66, v110
	v_mov_b32_e32 v67, v111
	v_mov_b32_e32 v64, v112
	v_mov_b32_e32 v65, v113
	s_barrier
	s_cbranch_vccz .LBB0_1219
.LBB0_1213:
	s_add_i32 s43, s0, s96
	s_cmpk_gt_i32 s43, 0x3ff
	s_cselect_b64 s[12:13], -1, 0
	s_and_b64 vcc, exec, s[12:13]
	v_mov_b32_e32 v51, v68
	v_mov_b32_e32 v53, v69
	v_mov_b32_e32 v55, v70
	v_mov_b32_e32 v101, v71
	v_mov_b32_e32 v102, v74
	v_mov_b32_e32 v103, v75
	v_mov_b32_e32 v104, v72
	v_mov_b32_e32 v105, v73
	v_mov_b32_e32 v106, v60
	v_mov_b32_e32 v107, v61
	v_mov_b32_e32 v108, v62
	v_mov_b32_e32 v109, v63
	v_mov_b32_e32 v110, v66
	v_mov_b32_e32 v111, v67
	v_mov_b32_e32 v112, v64
	v_mov_b32_e32 v113, v65
	s_cbranch_vccnz .LBB0_1215
	s_ashr_i32 s1, s43, 31
	s_lshr_b32 s1, s1, 30
	s_add_i32 s1, s43, s1
	s_ashr_i32 s1, s1, 2
	v_add_u32_e32 v2, s27, v92
	s_lshl_b32 s14, s1, 9
	v_subrev_u32_e32 v2, s14, v2
	s_lshl_b32 s16, s1, 6
	v_add_u32_e32 v2, 0xe00, v2
	v_or_b32_e32 v20, s16, v77
	v_mov_b32_e32 v3, v43
	v_lshl_add_u64 v[2:3], v[2:3], 1, s[4:5]
	v_or_b32_e32 v6, 1, v20
	v_or_b32_e32 v8, 2, v20
	v_or_b32_e32 v10, 3, v20
	v_or_b32_e32 v12, 4, v20
	v_or_b32_e32 v14, 5, v20
	v_or_b32_e32 v16, 6, v20
	v_or_b32_e32 v18, 7, v20
	v_mad_i64_i32 v[4:5], s[14:15], v20, s21, v[2:3]
	v_mad_i64_i32 v[6:7], s[14:15], v6, s21, v[2:3]
	v_mad_i64_i32 v[8:9], s[14:15], v8, s21, v[2:3]
	v_mad_i64_i32 v[10:11], s[14:15], v10, s21, v[2:3]
	v_mad_i64_i32 v[12:13], s[14:15], v12, s21, v[2:3]
	v_mad_i64_i32 v[14:15], s[14:15], v14, s21, v[2:3]
	v_mad_i64_i32 v[16:17], s[14:15], v16, s21, v[2:3]
	v_mad_i64_i32 v[18:19], s[14:15], v18, s21, v[2:3]
	global_load_ushort v214, v[6:7], off
	global_load_ushort v215, v[10:11], off
	global_load_ushort v216, v[14:15], off
	global_load_ushort v217, v[18:19], off
	global_load_ushort v218, v[16:17], off
	global_load_ushort v219, v[12:13], off
	global_load_ushort v220, v[8:9], off
	global_load_ushort v221, v[4:5], off
	v_or_b32_e32 v4, 8, v20
	v_or_b32_e32 v6, 9, v20
	v_or_b32_e32 v8, 10, v20
	v_or_b32_e32 v10, 11, v20
	v_or_b32_e32 v12, 12, v20
	v_or_b32_e32 v14, 13, v20
	v_or_b32_e32 v16, 14, v20
	v_or_b32_e32 v18, 15, v20
	v_mad_i64_i32 v[4:5], s[14:15], v4, s21, v[2:3]
	v_mad_i64_i32 v[6:7], s[14:15], v6, s21, v[2:3]
	v_mad_i64_i32 v[8:9], s[14:15], v8, s21, v[2:3]
	v_mad_i64_i32 v[10:11], s[14:15], v10, s21, v[2:3]
	v_mad_i64_i32 v[12:13], s[14:15], v12, s21, v[2:3]
	v_mad_i64_i32 v[14:15], s[14:15], v14, s21, v[2:3]
	v_mad_i64_i32 v[16:17], s[14:15], v16, s21, v[2:3]
	v_mad_i64_i32 v[2:3], s[14:15], v18, s21, v[2:3]
	v_readfirstlane_b32 s14, v76
	s_lshl_b32 s14, s14, 4
	s_add_i32 s14, s14, s16
	s_ashr_i32 s15, s14, 31
	s_lshl_b64 s[14:15], s[14:15], 6
	global_load_ushort v222, v[6:7], off
	global_load_ushort v223, v[10:11], off
	global_load_ushort v224, v[14:15], off
	global_load_ushort v225, v[2:3], off
	global_load_ushort v226, v[16:17], off
	global_load_ushort v227, v[12:13], off
	global_load_ushort v228, v[8:9], off
	global_load_ushort v229, v[4:5], off
	v_lshl_add_u64 v[2:3], v[48:49], 0, s[14:15]
	s_mul_i32 s14, s1, 0xe8000
	s_mul_hi_i32 s15, s16, 0x3a00
	s_add_u32 s16, s4, s14
	s_addc_u32 s17, s5, s15
	s_lshl_b32 s1, s1, 10
	s_sub_i32 s14, s29, s1
	s_ashr_i32 s15, s14, 31
	s_lshl_b64 s[14:15], s[14:15], 1
	s_add_u32 s14, s16, s14
	s_addc_u32 s15, s17, s15
	v_mov_b32_e32 v51, v43
	v_lshl_add_u64 v[4:5], s[14:15], 0, v[50:51]
	v_lshl_add_u64 v[10:11], v[4:5], 0, s[6:7]
	v_lshl_add_u64 v[18:19], v[4:5], 0, s[10:11]
	v_mov_b32_e32 v53, v43
	v_mov_b32_e32 v55, v43
	v_lshl_add_u64 v[4:5], v[10:11], 0, v[52:53]
	v_lshl_add_u64 v[12:13], v[18:19], 0, v[52:53]
	v_lshl_add_u64 v[14:15], v[10:11], 0, v[54:55]
	v_lshl_add_u64 v[18:19], v[18:19], 0, v[54:55]
	global_load_dwordx4 v[6:9], v[2:3], off
	s_nop 0
	global_load_dwordx4 v[2:5], v[4:5], off
	s_nop 0
	global_load_dwordx4 v[10:13], v[12:13], off
	s_nop 0
	global_load_dwordx4 v[14:17], v[14:15], off
	global_load_dwordx4 v[18:21], v[18:19], off
.LBB0_1215:
	s_ashr_i32 s1, s0, 31
	s_lshr_b32 s1, s1, 30
	s_add_i32 s1, s0, s1
	s_ashr_i32 s16, s1, 2
	s_and_b32 s1, s1, -4
	s_sub_i32 s14, s0, s1
	s_cmp_eq_u32 s14, s22
	s_cbranch_scc1 .LBB0_1217
	v_add_u32_e32 v44, s27, v1
	s_lshl_b32 s0, s16, 9
	v_readlane_b32 s44, v255, 13
	v_subrev_u32_e32 v44, s0, v44
	v_readlane_b32 s45, v255, 14
	v_readlane_b32 s46, v255, 15
	v_readlane_b32 s47, v255, 16
	v_readlane_b32 s48, v255, 17
	v_readlane_b32 s49, v255, 18
	v_readlane_b32 s50, v255, 19
	v_readlane_b32 s51, v255, 20
	v_readlane_b32 s52, v255, 21
	v_readlane_b32 s53, v255, 22
	v_ashrrev_i32_e32 v45, 31, v44
	v_readlane_b32 s54, v255, 23
	v_readlane_b32 s55, v255, 24
	v_readlane_b32 s56, v255, 25
	v_readlane_b32 s57, v255, 26
	s_mov_b64 s[44:45], s[48:49]
	v_lshlrev_b64 v[114:115], 2, v[44:45]
	s_mov_b64 s[46:47], s[50:51]
	s_mov_b64 s[48:49], s[52:53]
	v_lshl_add_u64 v[44:45], s[48:49], 0, v[114:115]
	v_add_co_u32_e32 v46, vcc, 0x1000, v44
	s_mov_b64 s[50:51], s[54:55]
	s_nop 0
	v_addc_co_u32_e32 v47, vcc, 0, v45, vcc
	v_add_co_u32_e32 v80, vcc, 0x2000, v44
	v_lshl_add_u64 v[114:115], s[50:51], 0, v[114:115]
	s_nop 0
	v_addc_co_u32_e32 v81, vcc, 0, v45, vcc
	v_add_co_u32_e32 v86, vcc, 0x3000, v44
	s_mov_b32 s22, s14
	s_nop 0
	v_addc_co_u32_e32 v87, vcc, 0, v45, vcc
	global_load_dword v82, v[44:45], off
	global_load_dword v83, v[44:45], off offset:2048
	global_load_dword v78, v[46:47], off
	global_load_dword v84, v[46:47], off offset:2048
	global_load_dword v79, v[80:81], off
	s_nop 0
	global_load_dword v80, v[80:81], off offset:2048
	s_nop 0
	global_load_dword v81, v[86:87], off
	global_load_dword v85, v[86:87], off offset:2048
	v_add_co_u32_e32 v46, vcc, 0x4000, v44
	v_readlane_b32 s58, v255, 27
	s_nop 0
	v_addc_co_u32_e32 v47, vcc, 0, v45, vcc
	v_add_co_u32_e32 v116, vcc, 0x5000, v44
	v_readlane_b32 s59, v255, 28
	s_nop 0
	v_addc_co_u32_e32 v117, vcc, 0, v45, vcc
	v_add_co_u32_e32 v118, vcc, 0x6000, v44
	s_mov_b64 s[52:53], s[56:57]
	s_nop 0
	v_addc_co_u32_e32 v119, vcc, 0, v45, vcc
	v_add_co_u32_e32 v120, vcc, 0x7000, v44
	s_nop 1
	v_addc_co_u32_e32 v121, vcc, 0, v45, vcc
	global_load_dword v86, v[46:47], off
	global_load_dword v87, v[46:47], off offset:2048
	global_load_dword v88, v[116:117], off
	global_load_dword v89, v[116:117], off offset:2048
	global_load_dword v44, v[118:119], off
	global_load_dword v45, v[118:119], off offset:2048
	s_nop 0
	global_load_dword v46, v[120:121], off
	global_load_dword v47, v[120:121], off offset:2048
	global_load_dword v100, v[114:115], off
	s_waitcnt vmcnt(0)
.LBB0_1217:
	v_readlane_b32 s0, v38, 0
	v_readlane_b32 s1, v39, 3
	s_ashr_i32 s17, s16, 31
	v_fma_f32 v57, s0, v82, v100
	v_readlane_b32 s0, v39, 0
	s_nop 1
	v_fmac_f32_e32 v57, s0, v83
	v_readlane_b32 s0, v40, 0
	s_nop 1
	v_fmac_f32_e32 v57, s0, v78
	v_readlane_b32 s0, v41, 0
	s_nop 1
	v_fmac_f32_e32 v57, s0, v84
	v_readlane_b32 s0, v38, 1
	s_nop 1
	v_fmac_f32_e32 v57, s0, v79
	v_readlane_b32 s0, v39, 1
	s_nop 1
	v_fmac_f32_e32 v57, s0, v80
	v_readlane_b32 s0, v40, 1
	s_nop 1
	v_fmac_f32_e32 v57, s0, v81
	v_readlane_b32 s0, v41, 1
	s_nop 1
	v_fmac_f32_e32 v57, s0, v85
	v_readlane_b32 s0, v38, 2
	s_nop 1
	v_fmac_f32_e32 v57, s0, v86
	v_readlane_b32 s0, v39, 2
	s_nop 1
	v_fmac_f32_e32 v57, s0, v87
	v_readlane_b32 s0, v40, 2
	s_nop 1
	v_fmac_f32_e32 v57, s0, v88
	v_readlane_b32 s0, v41, 2
	s_nop 1
	v_fmac_f32_e32 v57, s0, v89
	v_readlane_b32 s0, v38, 3
	s_nop 1
	v_pk_mul_f32 v[114:115], v[44:45], s[0:1]
	v_readlane_b32 s0, v40, 3
	v_add_f32_e32 v57, v57, v114
	v_readlane_b32 s1, v41, 3
	v_add_f32_e32 v57, v57, v115
	s_nop 0
	v_pk_mul_f32 v[114:115], v[46:47], s[0:1]
	v_readlane_b32 s0, v38, 4
	v_add_f32_e32 v57, v57, v114
	v_add_f32_e32 v57, v57, v115
	v_mul_f32_e64 v59, |v57|, s31
	v_exp_f32_e32 v59, v59
	v_fma_f32 v117, s0, v82, v100
	v_readlane_b32 s0, v39, 4
	v_readlane_b32 s1, v39, 7
	v_add_f32_e32 v59, 1.0, v59
	v_fmac_f32_e32 v117, s0, v83
	v_readlane_b32 s0, v40, 4
	v_cmp_gt_f32_e32 vcc, s34, v59
	v_min_f32_e32 v57, 0, v57
	v_fmac_f32_e32 v117, s0, v78
	v_readlane_b32 s0, v41, 4
	v_cndmask_b32_e64 v114, 0, 32, vcc
	v_ldexp_f32 v59, v59, v114
	v_fmac_f32_e32 v117, s0, v84
	v_readlane_b32 s0, v38, 5
	v_log_f32_e32 v59, v59
	s_nop 0
	v_fmac_f32_e32 v117, s0, v79
	v_readlane_b32 s0, v39, 5
	v_mul_f32_e32 v114, 0x3f317217, v59
	v_fma_f32 v116, v59, s35, -v114
	v_fmac_f32_e32 v117, s0, v80
	v_readlane_b32 s0, v40, 5
	v_fmac_f32_e32 v116, 0x3377d1cf, v59
	v_fmac_f32_e32 v116, 0x3f317217, v59
	v_fmac_f32_e32 v117, s0, v81
	v_readlane_b32 s0, v41, 5
	s_nop 1
	v_fmac_f32_e32 v117, s0, v85
	v_readlane_b32 s0, v38, 6
	s_nop 1
	v_fmac_f32_e32 v117, s0, v86
	v_readlane_b32 s0, v39, 6
	s_nop 1
	v_fmac_f32_e32 v117, s0, v87
	v_readlane_b32 s0, v40, 6
	s_nop 1
	v_fmac_f32_e32 v117, s0, v88
	v_readlane_b32 s0, v41, 6
	s_nop 1
	v_fmac_f32_e32 v117, s0, v89
	v_readlane_b32 s0, v38, 7
	s_nop 1
	v_pk_mul_f32 v[114:115], v[44:45], s[0:1]
	v_readlane_b32 s0, v40, 7
	v_add_f32_e32 v114, v117, v114
	v_readlane_b32 s1, v41, 7
	v_add_f32_e32 v117, v114, v115
	s_nop 0
	v_pk_mul_f32 v[114:115], v[46:47], s[0:1]
	v_cmp_lt_f32_e64 s[0:1], |v59|, s36
	v_add_f32_e32 v114, v117, v114
	v_add_f32_e32 v114, v114, v115
	v_mul_f32_e64 v115, |v114|, s31
	v_exp_f32_e32 v115, v115
	v_cndmask_b32_e64 v59, v59, v116, s[0:1]
	v_readlane_b32 s0, v38, 8
	v_cndmask_b32_e32 v116, 0, v99, vcc
	v_add_f32_e32 v115, 1.0, v115
	v_fma_f32 v118, s0, v82, v100
	v_readlane_b32 s0, v39, 8
	v_cmp_gt_f32_e32 vcc, s34, v115
	v_sub_f32_e32 v59, v59, v116
	v_fmac_f32_e32 v118, s0, v83
	v_readlane_b32 s0, v40, 8
	v_cndmask_b32_e64 v116, 0, 32, vcc
	v_ldexp_f32 v115, v115, v116
	v_fmac_f32_e32 v118, s0, v78
	v_readlane_b32 s0, v41, 8
	v_log_f32_e32 v116, v115
	v_sub_f32_e32 v57, v57, v59
	v_fmac_f32_e32 v118, s0, v84
	v_readlane_b32 s0, v38, 9
	v_min_f32_e32 v59, 0, v114
	v_mul_f32_e32 v114, 0x3f317217, v116
	v_fmac_f32_e32 v118, s0, v79
	v_readlane_b32 s0, v39, 9
	v_readlane_b32 s1, v39, 11
	v_fma_f32 v117, v116, s35, -v114
	v_fmac_f32_e32 v118, s0, v80
	v_readlane_b32 s0, v40, 9
	v_fmac_f32_e32 v117, 0x3377d1cf, v116
	v_fmac_f32_e32 v117, 0x3f317217, v116
	v_fmac_f32_e32 v118, s0, v81
	v_readlane_b32 s0, v41, 9
	v_fma_f32 v57, v57, s37, 0
	s_nop 0
	v_fmac_f32_e32 v118, s0, v85
	v_readlane_b32 s0, v38, 10
	s_nop 1
	v_fmac_f32_e32 v118, s0, v86
	v_readlane_b32 s0, v39, 10
	s_nop 1
	v_fmac_f32_e32 v118, s0, v87
	v_readlane_b32 s0, v40, 10
	s_nop 1
	v_fmac_f32_e32 v118, s0, v88
	v_readlane_b32 s0, v41, 10
	s_nop 1
	v_fmac_f32_e32 v118, s0, v89
	v_readlane_b32 s0, v38, 11
	s_nop 1
	v_pk_mul_f32 v[114:115], v[44:45], s[0:1]
	v_readlane_b32 s0, v40, 11
	v_add_f32_e32 v114, v118, v114
	v_readlane_b32 s1, v41, 11
	v_add_f32_e32 v118, v114, v115
	s_nop 0
	v_pk_mul_f32 v[114:115], v[46:47], s[0:1]
	v_cmp_lt_f32_e64 s[0:1], |v116|, s36
	v_add_f32_e32 v114, v118, v114
	v_add_f32_e32 v114, v114, v115
	v_mul_f32_e64 v115, |v114|, s31
	v_exp_f32_e32 v115, v115
	v_cndmask_b32_e64 v116, v116, v117, s[0:1]
	v_readlane_b32 s0, v38, 12
	v_cndmask_b32_e32 v117, 0, v99, vcc
	v_add_f32_e32 v115, 1.0, v115
	v_fma_f32 v119, s0, v82, v100
	v_readlane_b32 s0, v39, 12
	v_cmp_gt_f32_e32 vcc, s34, v115
	v_sub_f32_e32 v116, v116, v117
	v_fmac_f32_e32 v119, s0, v83
	v_readlane_b32 s0, v40, 12
	v_cndmask_b32_e64 v117, 0, 32, vcc
	v_ldexp_f32 v115, v115, v117
	v_fmac_f32_e32 v119, s0, v78
	v_readlane_b32 s0, v41, 12
	v_log_f32_e32 v117, v115
	v_sub_f32_e32 v59, v59, v116
	v_fmac_f32_e32 v119, s0, v84
	v_readlane_b32 s0, v38, 13
	v_min_f32_e32 v116, 0, v114
	v_mul_f32_e32 v114, 0x3f317217, v117
	v_fmac_f32_e32 v119, s0, v79
	v_readlane_b32 s0, v39, 13
	v_readlane_b32 s1, v39, 15
	v_fma_f32 v118, v117, s35, -v114
	v_fmac_f32_e32 v119, s0, v80
	v_readlane_b32 s0, v40, 13
	v_fmac_f32_e32 v118, 0x3377d1cf, v117
	v_fmac_f32_e32 v118, 0x3f317217, v117
	v_fmac_f32_e32 v119, s0, v81
	v_readlane_b32 s0, v41, 13
	v_fmamk_f32 v59, v59, 0x3d800000, v57
	s_nop 0
	v_fmac_f32_e32 v119, s0, v85
	v_readlane_b32 s0, v38, 14
	s_nop 1
	v_fmac_f32_e32 v119, s0, v86
	v_readlane_b32 s0, v39, 14
	s_nop 1
	v_fmac_f32_e32 v119, s0, v87
	v_readlane_b32 s0, v40, 14
	s_nop 1
	v_fmac_f32_e32 v119, s0, v88
	v_readlane_b32 s0, v41, 14
	s_nop 1
	v_fmac_f32_e32 v119, s0, v89
	v_readlane_b32 s0, v38, 15
	s_nop 1
	v_pk_mul_f32 v[114:115], v[44:45], s[0:1]
	v_readlane_b32 s0, v40, 15
	v_add_f32_e32 v114, v119, v114
	v_readlane_b32 s1, v41, 15
	v_add_f32_e32 v119, v114, v115
	s_nop 0
	v_pk_mul_f32 v[114:115], v[46:47], s[0:1]
	v_cmp_lt_f32_e64 s[0:1], |v117|, s36
	v_add_f32_e32 v114, v119, v114
	v_add_f32_e32 v115, v114, v115
	v_mul_f32_e64 v114, |v115|, s31
	v_exp_f32_e32 v114, v114
	v_cndmask_b32_e64 v117, v117, v118, s[0:1]
	v_readlane_b32 s0, v38, 16
	v_cndmask_b32_e32 v118, 0, v99, vcc
	v_add_f32_e32 v114, 1.0, v114
	v_fma_f32 v120, s0, v82, v100
	v_readlane_b32 s0, v39, 16
	v_cmp_gt_f32_e32 vcc, s34, v114
	v_sub_f32_e32 v117, v117, v118
	v_fmac_f32_e32 v120, s0, v83
	v_readlane_b32 s0, v40, 16
	v_cndmask_b32_e64 v118, 0, 32, vcc
	v_ldexp_f32 v114, v114, v118
	v_fmac_f32_e32 v120, s0, v78
	v_readlane_b32 s0, v41, 16
	v_log_f32_e32 v118, v114
	v_sub_f32_e32 v114, v116, v117
	v_fmac_f32_e32 v120, s0, v84
	v_readlane_b32 s0, v38, 17
	v_mul_f32_e32 v116, 0x3f317217, v118
	v_readlane_b32 s1, v39, 19
	v_fmac_f32_e32 v120, s0, v79
	v_readlane_b32 s0, v39, 17
	v_fma_f32 v119, v118, s35, -v116
	v_fmac_f32_e32 v119, 0x3377d1cf, v118
	v_fmac_f32_e32 v120, s0, v80
	v_readlane_b32 s0, v40, 17
	v_fmac_f32_e32 v119, 0x3f317217, v118
	v_min_f32_e32 v115, 0, v115
	v_fmac_f32_e32 v120, s0, v81
	v_readlane_b32 s0, v41, 17
	v_fmamk_f32 v114, v114, 0x3d800000, v59
	s_nop 0
	v_fmac_f32_e32 v120, s0, v85
	v_readlane_b32 s0, v38, 18
	s_nop 1
	v_fmac_f32_e32 v120, s0, v86
	v_readlane_b32 s0, v39, 18
	s_nop 1
	v_fmac_f32_e32 v120, s0, v87
	v_readlane_b32 s0, v40, 18
	s_nop 1
	v_fmac_f32_e32 v120, s0, v88
	v_readlane_b32 s0, v41, 18
	s_nop 1
	v_fmac_f32_e32 v120, s0, v89
	v_readlane_b32 s0, v38, 19
	s_nop 1
	v_pk_mul_f32 v[116:117], v[44:45], s[0:1]
	v_readlane_b32 s0, v40, 19
	v_add_f32_e32 v116, v120, v116
	v_readlane_b32 s1, v41, 19
	v_add_f32_e32 v120, v116, v117
	s_nop 0
	v_pk_mul_f32 v[116:117], v[46:47], s[0:1]
	v_cmp_lt_f32_e64 s[0:1], |v118|, s36
	v_add_f32_e32 v116, v120, v116
	v_add_f32_e32 v116, v116, v117
	v_mul_f32_e64 v117, |v116|, s31
	v_exp_f32_e32 v117, v117
	v_cndmask_b32_e64 v118, v118, v119, s[0:1]
	v_readlane_b32 s0, v38, 20
	v_cndmask_b32_e32 v119, 0, v99, vcc
	v_add_f32_e32 v117, 1.0, v117
	v_fma_f32 v121, s0, v82, v100
	v_readlane_b32 s0, v39, 20
	v_cmp_gt_f32_e32 vcc, s34, v117
	v_sub_f32_e32 v118, v118, v119
	v_fmac_f32_e32 v121, s0, v83
	v_readlane_b32 s0, v40, 20
	v_cndmask_b32_e64 v119, 0, 32, vcc
	v_ldexp_f32 v117, v117, v119
	v_fmac_f32_e32 v121, s0, v78
	v_readlane_b32 s0, v41, 20
	v_log_f32_e32 v119, v117
	v_sub_f32_e32 v115, v115, v118
	v_fmac_f32_e32 v121, s0, v84
	v_readlane_b32 s0, v38, 21
	v_min_f32_e32 v118, 0, v116
	v_mul_f32_e32 v116, 0x3f317217, v119
	v_fmac_f32_e32 v121, s0, v79
	v_readlane_b32 s0, v39, 21
	v_readlane_b32 s1, v39, 23
	v_fma_f32 v120, v119, s35, -v116
	v_fmac_f32_e32 v121, s0, v80
	v_readlane_b32 s0, v40, 21
	v_fmac_f32_e32 v120, 0x3377d1cf, v119
	v_fmac_f32_e32 v120, 0x3f317217, v119
	v_fmac_f32_e32 v121, s0, v81
	v_readlane_b32 s0, v41, 21
	v_fmamk_f32 v115, v115, 0x3d800000, v114
	s_nop 0
	v_fmac_f32_e32 v121, s0, v85
	v_readlane_b32 s0, v38, 22
	s_nop 1
	v_fmac_f32_e32 v121, s0, v86
	v_readlane_b32 s0, v39, 22
	s_nop 1
	v_fmac_f32_e32 v121, s0, v87
	v_readlane_b32 s0, v40, 22
	s_nop 1
	v_fmac_f32_e32 v121, s0, v88
	v_readlane_b32 s0, v41, 22
	s_nop 1
	v_fmac_f32_e32 v121, s0, v89
	v_readlane_b32 s0, v38, 23
	s_nop 1
	v_pk_mul_f32 v[116:117], v[44:45], s[0:1]
	v_readlane_b32 s0, v40, 23
	v_add_f32_e32 v116, v121, v116
	v_readlane_b32 s1, v41, 23
	v_add_f32_e32 v121, v116, v117
	s_nop 0
	v_pk_mul_f32 v[116:117], v[46:47], s[0:1]
	v_cmp_lt_f32_e64 s[0:1], |v119|, s36
	v_add_f32_e32 v116, v121, v116
	v_add_f32_e32 v117, v116, v117
	v_mul_f32_e64 v116, |v117|, s31
	v_exp_f32_e32 v116, v116
	v_cndmask_b32_e64 v119, v119, v120, s[0:1]
	v_readlane_b32 s0, v38, 24
	v_cndmask_b32_e32 v120, 0, v99, vcc
	v_add_f32_e32 v116, 1.0, v116
	v_fma_f32 v122, s0, v82, v100
	v_readlane_b32 s0, v39, 24
	v_cmp_gt_f32_e32 vcc, s34, v116
	v_sub_f32_e32 v119, v119, v120
	v_fmac_f32_e32 v122, s0, v83
	v_readlane_b32 s0, v40, 24
	v_cndmask_b32_e64 v120, 0, 32, vcc
	v_ldexp_f32 v116, v116, v120
	v_fmac_f32_e32 v122, s0, v78
	v_readlane_b32 s0, v41, 24
	v_log_f32_e32 v120, v116
	v_sub_f32_e32 v116, v118, v119
	v_fmac_f32_e32 v122, s0, v84
	v_readlane_b32 s0, v38, 25
	v_mul_f32_e32 v118, 0x3f317217, v120
	v_readlane_b32 s1, v39, 27
	v_fmac_f32_e32 v122, s0, v79
	v_readlane_b32 s0, v39, 25
	v_fma_f32 v121, v120, s35, -v118
	v_fmac_f32_e32 v121, 0x3377d1cf, v120
	v_fmac_f32_e32 v122, s0, v80
	v_readlane_b32 s0, v40, 25
	v_fmac_f32_e32 v121, 0x3f317217, v120
	v_min_f32_e32 v117, 0, v117
	v_fmac_f32_e32 v122, s0, v81
	v_readlane_b32 s0, v41, 25
	v_fmamk_f32 v116, v116, 0x3d800000, v115
	s_nop 0
	v_fmac_f32_e32 v122, s0, v85
	v_readlane_b32 s0, v38, 26
	s_nop 1
	v_fmac_f32_e32 v122, s0, v86
	v_readlane_b32 s0, v39, 26
	s_nop 1
	v_fmac_f32_e32 v122, s0, v87
	v_readlane_b32 s0, v40, 26
	s_nop 1
	v_fmac_f32_e32 v122, s0, v88
	v_readlane_b32 s0, v41, 26
	s_nop 1
	v_fmac_f32_e32 v122, s0, v89
	v_readlane_b32 s0, v38, 27
	s_nop 1
	v_pk_mul_f32 v[118:119], v[44:45], s[0:1]
	v_readlane_b32 s0, v40, 27
	v_add_f32_e32 v118, v122, v118
	v_readlane_b32 s1, v41, 27
	v_add_f32_e32 v122, v118, v119
	s_nop 0
	v_pk_mul_f32 v[118:119], v[46:47], s[0:1]
	v_cmp_lt_f32_e64 s[0:1], |v120|, s36
	v_add_f32_e32 v118, v122, v118
	v_add_f32_e32 v118, v118, v119
	v_mul_f32_e64 v119, |v118|, s31
	v_exp_f32_e32 v119, v119
	v_cndmask_b32_e64 v120, v120, v121, s[0:1]
	v_readlane_b32 s0, v38, 28
	v_cndmask_b32_e32 v121, 0, v99, vcc
	v_add_f32_e32 v119, 1.0, v119
	v_fma_f32 v123, s0, v82, v100
	v_readlane_b32 s0, v39, 28
	v_cmp_gt_f32_e32 vcc, s34, v119
	v_sub_f32_e32 v120, v120, v121
	v_fmac_f32_e32 v123, s0, v83
	v_readlane_b32 s0, v40, 28
	v_cndmask_b32_e64 v121, 0, 32, vcc
	v_ldexp_f32 v119, v119, v121
	v_fmac_f32_e32 v123, s0, v78
	v_readlane_b32 s0, v41, 28
	v_log_f32_e32 v121, v119
	v_sub_f32_e32 v117, v117, v120
	v_fmac_f32_e32 v123, s0, v84
	v_readlane_b32 s0, v38, 29
	v_min_f32_e32 v120, 0, v118
	v_mul_f32_e32 v118, 0x3f317217, v121
	v_fmac_f32_e32 v123, s0, v79
	v_readlane_b32 s0, v39, 29
	v_readlane_b32 s1, v39, 31
	v_fma_f32 v122, v121, s35, -v118
	v_fmac_f32_e32 v123, s0, v80
	v_readlane_b32 s0, v40, 29
	v_fmac_f32_e32 v122, 0x3377d1cf, v121
	v_fmac_f32_e32 v122, 0x3f317217, v121
	v_fmac_f32_e32 v123, s0, v81
	v_readlane_b32 s0, v41, 29
	v_fmamk_f32 v117, v117, 0x3d800000, v116
	s_nop 0
	v_fmac_f32_e32 v123, s0, v85
	v_readlane_b32 s0, v38, 30
	s_nop 1
	v_fmac_f32_e32 v123, s0, v86
	v_readlane_b32 s0, v39, 30
	s_nop 1
	v_fmac_f32_e32 v123, s0, v87
	v_readlane_b32 s0, v40, 30
	s_nop 1
	v_fmac_f32_e32 v123, s0, v88
	v_readlane_b32 s0, v41, 30
	s_nop 1
	v_fmac_f32_e32 v123, s0, v89
	v_readlane_b32 s0, v38, 31
	s_nop 1
	v_pk_mul_f32 v[118:119], v[44:45], s[0:1]
	v_readlane_b32 s0, v40, 31
	v_add_f32_e32 v118, v123, v118
	v_readlane_b32 s1, v41, 31
	v_add_f32_e32 v123, v118, v119
	s_nop 0
	v_pk_mul_f32 v[118:119], v[46:47], s[0:1]
	v_cmp_lt_f32_e64 s[0:1], |v121|, s36
	v_add_f32_e32 v118, v123, v118
	v_add_f32_e32 v119, v118, v119
	v_mul_f32_e64 v118, |v119|, s31
	v_exp_f32_e32 v118, v118
	v_cndmask_b32_e64 v121, v121, v122, s[0:1]
	v_readlane_b32 s0, v38, 32
	v_cndmask_b32_e32 v122, 0, v99, vcc
	v_add_f32_e32 v118, 1.0, v118
	v_fma_f32 v124, s0, v82, v100
	v_readlane_b32 s0, v39, 32
	v_cmp_gt_f32_e32 vcc, s34, v118
	v_sub_f32_e32 v121, v121, v122
	v_fmac_f32_e32 v124, s0, v83
	v_readlane_b32 s0, v40, 32
	v_cndmask_b32_e64 v122, 0, 32, vcc
	v_ldexp_f32 v118, v118, v122
	v_fmac_f32_e32 v124, s0, v78
	v_readlane_b32 s0, v41, 32
	v_log_f32_e32 v122, v118
	v_sub_f32_e32 v118, v120, v121
	v_fmac_f32_e32 v124, s0, v84
	v_readlane_b32 s0, v38, 33
	v_mul_f32_e32 v120, 0x3f317217, v122
	v_readlane_b32 s1, v39, 35
	v_fmac_f32_e32 v124, s0, v79
	v_readlane_b32 s0, v39, 33
	v_fma_f32 v123, v122, s35, -v120
	v_fmac_f32_e32 v123, 0x3377d1cf, v122
	v_fmac_f32_e32 v124, s0, v80
	v_readlane_b32 s0, v40, 33
	v_fmac_f32_e32 v123, 0x3f317217, v122
	v_min_f32_e32 v119, 0, v119
	v_fmac_f32_e32 v124, s0, v81
	v_readlane_b32 s0, v41, 33
	v_fmamk_f32 v118, v118, 0x3d800000, v117
	s_nop 0
	v_fmac_f32_e32 v124, s0, v85
	v_readlane_b32 s0, v38, 34
	s_nop 1
	v_fmac_f32_e32 v124, s0, v86
	v_readlane_b32 s0, v39, 34
	s_nop 1
	v_fmac_f32_e32 v124, s0, v87
	v_readlane_b32 s0, v40, 34
	s_nop 1
	v_fmac_f32_e32 v124, s0, v88
	v_readlane_b32 s0, v41, 34
	s_nop 1
	v_fmac_f32_e32 v124, s0, v89
	v_readlane_b32 s0, v38, 35
	s_nop 1
	v_pk_mul_f32 v[120:121], v[44:45], s[0:1]
	v_readlane_b32 s0, v40, 35
	v_add_f32_e32 v120, v124, v120
	v_readlane_b32 s1, v41, 35
	v_add_f32_e32 v124, v120, v121
	s_nop 0
	v_pk_mul_f32 v[120:121], v[46:47], s[0:1]
	v_cmp_lt_f32_e64 s[0:1], |v122|, s36
	v_add_f32_e32 v120, v124, v120
	v_add_f32_e32 v120, v120, v121
	v_mul_f32_e64 v121, |v120|, s31
	v_exp_f32_e32 v121, v121
	v_cndmask_b32_e64 v122, v122, v123, s[0:1]
	v_readlane_b32 s0, v38, 36
	v_cndmask_b32_e32 v123, 0, v99, vcc
	v_add_f32_e32 v121, 1.0, v121
	v_fma_f32 v125, s0, v82, v100
	v_readlane_b32 s0, v39, 36
	v_cmp_gt_f32_e32 vcc, s34, v121
	v_sub_f32_e32 v122, v122, v123
	v_fmac_f32_e32 v125, s0, v83
	v_readlane_b32 s0, v40, 36
	v_cndmask_b32_e64 v123, 0, 32, vcc
	v_ldexp_f32 v121, v121, v123
	v_fmac_f32_e32 v125, s0, v78
	v_readlane_b32 s0, v41, 36
	v_log_f32_e32 v123, v121
	v_sub_f32_e32 v119, v119, v122
	v_fmac_f32_e32 v125, s0, v84
	v_readlane_b32 s0, v38, 37
	v_min_f32_e32 v122, 0, v120
	v_mul_f32_e32 v120, 0x3f317217, v123
	v_fmac_f32_e32 v125, s0, v79
	v_readlane_b32 s0, v39, 37
	v_readlane_b32 s1, v39, 39
	v_fma_f32 v124, v123, s35, -v120
	v_fmac_f32_e32 v125, s0, v80
	v_readlane_b32 s0, v40, 37
	v_fmac_f32_e32 v124, 0x3377d1cf, v123
	v_fmac_f32_e32 v124, 0x3f317217, v123
	v_fmac_f32_e32 v125, s0, v81
	v_readlane_b32 s0, v41, 37
	v_fmamk_f32 v119, v119, 0x3d800000, v118
	s_nop 0
	v_fmac_f32_e32 v125, s0, v85
	v_readlane_b32 s0, v38, 38
	s_nop 1
	v_fmac_f32_e32 v125, s0, v86
	v_readlane_b32 s0, v39, 38
	s_nop 1
	v_fmac_f32_e32 v125, s0, v87
	v_readlane_b32 s0, v40, 38
	s_nop 1
	v_fmac_f32_e32 v125, s0, v88
	v_readlane_b32 s0, v41, 38
	s_nop 1
	v_fmac_f32_e32 v125, s0, v89
	v_readlane_b32 s0, v38, 39
	s_nop 1
	v_pk_mul_f32 v[120:121], v[44:45], s[0:1]
	v_readlane_b32 s0, v40, 39
	v_add_f32_e32 v120, v125, v120
	v_readlane_b32 s1, v41, 39
	v_add_f32_e32 v125, v120, v121
	s_nop 0
	v_pk_mul_f32 v[120:121], v[46:47], s[0:1]
	v_cmp_lt_f32_e64 s[0:1], |v123|, s36
	v_add_f32_e32 v120, v125, v120
	v_add_f32_e32 v121, v120, v121
	v_mul_f32_e64 v120, |v121|, s31
	v_exp_f32_e32 v120, v120
	v_cndmask_b32_e64 v123, v123, v124, s[0:1]
	v_readlane_b32 s0, v38, 40
	v_cndmask_b32_e32 v124, 0, v99, vcc
	v_add_f32_e32 v120, 1.0, v120
	v_fma_f32 v126, s0, v82, v100
	v_readlane_b32 s0, v39, 40
	v_cmp_gt_f32_e32 vcc, s34, v120
	v_sub_f32_e32 v123, v123, v124
	v_fmac_f32_e32 v126, s0, v83
	v_readlane_b32 s0, v40, 40
	v_cndmask_b32_e64 v124, 0, 32, vcc
	v_ldexp_f32 v120, v120, v124
	v_fmac_f32_e32 v126, s0, v78
	v_readlane_b32 s0, v41, 40
	v_log_f32_e32 v124, v120
	v_sub_f32_e32 v120, v122, v123
	v_fmac_f32_e32 v126, s0, v84
	v_readlane_b32 s0, v38, 41
	v_mul_f32_e32 v122, 0x3f317217, v124
	v_readlane_b32 s1, v39, 43
	v_fmac_f32_e32 v126, s0, v79
	v_readlane_b32 s0, v39, 41
	v_fma_f32 v125, v124, s35, -v122
	v_fmac_f32_e32 v125, 0x3377d1cf, v124
	v_fmac_f32_e32 v126, s0, v80
	v_readlane_b32 s0, v40, 41
	v_fmac_f32_e32 v125, 0x3f317217, v124
	v_min_f32_e32 v121, 0, v121
	v_fmac_f32_e32 v126, s0, v81
	v_readlane_b32 s0, v41, 41
	v_fmamk_f32 v120, v120, 0x3d800000, v119
	s_nop 0
	v_fmac_f32_e32 v126, s0, v85
	v_readlane_b32 s0, v38, 42
	s_nop 1
	v_fmac_f32_e32 v126, s0, v86
	v_readlane_b32 s0, v39, 42
	s_nop 1
	v_fmac_f32_e32 v126, s0, v87
	v_readlane_b32 s0, v40, 42
	s_nop 1
	v_fmac_f32_e32 v126, s0, v88
	v_readlane_b32 s0, v41, 42
	s_nop 1
	v_fmac_f32_e32 v126, s0, v89
	v_readlane_b32 s0, v38, 43
	s_nop 1
	v_pk_mul_f32 v[122:123], v[44:45], s[0:1]
	v_readlane_b32 s0, v40, 43
	v_add_f32_e32 v122, v126, v122
	v_readlane_b32 s1, v41, 43
	v_add_f32_e32 v126, v122, v123
	s_nop 0
	v_pk_mul_f32 v[122:123], v[46:47], s[0:1]
	v_cmp_lt_f32_e64 s[0:1], |v124|, s36
	v_add_f32_e32 v122, v126, v122
	v_add_f32_e32 v122, v122, v123
	v_mul_f32_e64 v123, |v122|, s31
	v_exp_f32_e32 v123, v123
	v_cndmask_b32_e64 v124, v124, v125, s[0:1]
	v_readlane_b32 s0, v38, 44
	v_cndmask_b32_e32 v125, 0, v99, vcc
	v_add_f32_e32 v123, 1.0, v123
	v_fma_f32 v127, s0, v82, v100
	v_readlane_b32 s0, v39, 44
	v_cmp_gt_f32_e32 vcc, s34, v123
	v_sub_f32_e32 v124, v124, v125
	v_fmac_f32_e32 v127, s0, v83
	v_readlane_b32 s0, v40, 44
	v_cndmask_b32_e64 v125, 0, 32, vcc
	v_ldexp_f32 v123, v123, v125
	v_fmac_f32_e32 v127, s0, v78
	v_readlane_b32 s0, v41, 44
	v_log_f32_e32 v125, v123
	v_sub_f32_e32 v121, v121, v124
	v_fmac_f32_e32 v127, s0, v84
	v_readlane_b32 s0, v38, 45
	v_min_f32_e32 v124, 0, v122
	v_mul_f32_e32 v122, 0x3f317217, v125
	v_fmac_f32_e32 v127, s0, v79
	v_readlane_b32 s0, v39, 45
	v_readlane_b32 s1, v39, 47
	v_fma_f32 v126, v125, s35, -v122
	v_fmac_f32_e32 v127, s0, v80
	v_readlane_b32 s0, v40, 45
	v_fmac_f32_e32 v126, 0x3377d1cf, v125
	v_fmac_f32_e32 v126, 0x3f317217, v125
	v_fmac_f32_e32 v127, s0, v81
	v_readlane_b32 s0, v41, 45
	v_fmamk_f32 v121, v121, 0x3d800000, v120
	s_nop 0
	v_fmac_f32_e32 v127, s0, v85
	v_readlane_b32 s0, v38, 46
	s_nop 1
	v_fmac_f32_e32 v127, s0, v86
	v_readlane_b32 s0, v39, 46
	s_nop 1
	v_fmac_f32_e32 v127, s0, v87
	v_readlane_b32 s0, v40, 46
	s_nop 1
	v_fmac_f32_e32 v127, s0, v88
	v_readlane_b32 s0, v41, 46
	s_nop 1
	v_fmac_f32_e32 v127, s0, v89
	v_readlane_b32 s0, v38, 47
	s_nop 1
	v_pk_mul_f32 v[122:123], v[44:45], s[0:1]
	v_readlane_b32 s0, v40, 47
	v_add_f32_e32 v122, v127, v122
	v_readlane_b32 s1, v41, 47
	v_add_f32_e32 v127, v122, v123
	s_nop 0
	v_pk_mul_f32 v[122:123], v[46:47], s[0:1]
	v_cmp_lt_f32_e64 s[0:1], |v125|, s36
	v_add_f32_e32 v122, v127, v122
	v_add_f32_e32 v122, v122, v123
	v_mul_f32_e64 v123, |v122|, s31
	v_exp_f32_e32 v123, v123
	v_cndmask_b32_e64 v125, v125, v126, s[0:1]
	v_readlane_b32 s0, v38, 48
	v_cndmask_b32_e32 v126, 0, v99, vcc
	v_add_f32_e32 v123, 1.0, v123
	v_fma_f32 v128, s0, v82, v100
	v_readlane_b32 s0, v39, 48
	v_cmp_gt_f32_e32 vcc, s34, v123
	v_sub_f32_e32 v125, v125, v126
	v_fmac_f32_e32 v128, s0, v83
	v_readlane_b32 s0, v40, 48
	v_cndmask_b32_e64 v126, 0, 32, vcc
	v_ldexp_f32 v123, v123, v126
	v_fmac_f32_e32 v128, s0, v78
	v_readlane_b32 s0, v41, 48
	v_log_f32_e32 v126, v123
	v_sub_f32_e32 v123, v124, v125
	v_fmac_f32_e32 v128, s0, v84
	v_readlane_b32 s0, v38, 49
	v_min_f32_e32 v125, 0, v122
	v_mul_f32_e32 v122, 0x3f317217, v126
	v_fmac_f32_e32 v128, s0, v79
	v_readlane_b32 s0, v39, 49
	v_readlane_b32 s1, v39, 51
	v_fmamk_f32 v124, v123, 0x3d800000, v121
	v_fmac_f32_e32 v128, s0, v80
	v_readlane_b32 s0, v40, 49
	v_fma_f32 v127, v126, s35, -v122
	v_fmac_f32_e32 v127, 0x3377d1cf, v126
	v_fmac_f32_e32 v128, s0, v81
	v_readlane_b32 s0, v41, 49
	v_fmac_f32_e32 v127, 0x3f317217, v126
	s_nop 0
	v_fmac_f32_e32 v128, s0, v85
	v_readlane_b32 s0, v38, 50
	s_nop 1
	v_fmac_f32_e32 v128, s0, v86
	v_readlane_b32 s0, v39, 50
	s_nop 1
	v_fmac_f32_e32 v128, s0, v87
	v_readlane_b32 s0, v40, 50
	s_nop 1
	v_fmac_f32_e32 v128, s0, v88
	v_readlane_b32 s0, v41, 50
	s_nop 1
	v_fmac_f32_e32 v128, s0, v89
	v_readlane_b32 s0, v38, 51
	s_nop 1
	v_pk_mul_f32 v[122:123], v[44:45], s[0:1]
	v_readlane_b32 s0, v40, 51
	v_add_f32_e32 v122, v128, v122
	v_readlane_b32 s1, v41, 51
	v_add_f32_e32 v128, v122, v123
	s_nop 0
	v_pk_mul_f32 v[122:123], v[46:47], s[0:1]
	v_cmp_lt_f32_e64 s[0:1], |v126|, s36
	v_add_f32_e32 v122, v128, v122
	v_add_f32_e32 v122, v122, v123
	v_mul_f32_e64 v123, |v122|, s31
	v_exp_f32_e32 v123, v123
	v_cndmask_b32_e64 v126, v126, v127, s[0:1]
	v_readlane_b32 s0, v38, 52
	v_cndmask_b32_e32 v127, 0, v99, vcc
	v_add_f32_e32 v123, 1.0, v123
	v_fma_f32 v129, s0, v82, v100
	v_readlane_b32 s0, v39, 52
	v_cmp_gt_f32_e32 vcc, s34, v123
	v_sub_f32_e32 v126, v126, v127
	v_fmac_f32_e32 v129, s0, v83
	v_readlane_b32 s0, v40, 52
	v_cndmask_b32_e64 v127, 0, 32, vcc
	v_ldexp_f32 v123, v123, v127
	v_fmac_f32_e32 v129, s0, v78
	v_readlane_b32 s0, v41, 52
	v_log_f32_e32 v127, v123
	v_sub_f32_e32 v123, v125, v126
	v_fmac_f32_e32 v129, s0, v84
	v_readlane_b32 s0, v38, 53
	v_min_f32_e32 v126, 0, v122
	v_mul_f32_e32 v122, 0x3f317217, v127
	v_fmac_f32_e32 v129, s0, v79
	v_readlane_b32 s0, v39, 53
	v_readlane_b32 s1, v39, 55
	v_fmamk_f32 v125, v123, 0x3d800000, v124
	v_fmac_f32_e32 v129, s0, v80
	v_readlane_b32 s0, v40, 53
	v_fma_f32 v128, v127, s35, -v122
	v_fmac_f32_e32 v128, 0x3377d1cf, v127
	v_fmac_f32_e32 v129, s0, v81
	v_readlane_b32 s0, v41, 53
	v_fmac_f32_e32 v128, 0x3f317217, v127
	s_nop 0
	v_fmac_f32_e32 v129, s0, v85
	v_readlane_b32 s0, v38, 54
	s_nop 1
	v_fmac_f32_e32 v129, s0, v86
	v_readlane_b32 s0, v39, 54
	s_nop 1
	v_fmac_f32_e32 v129, s0, v87
	v_readlane_b32 s0, v40, 54
	s_nop 1
	v_fmac_f32_e32 v129, s0, v88
	v_readlane_b32 s0, v41, 54
	s_nop 1
	v_fmac_f32_e32 v129, s0, v89
	v_readlane_b32 s0, v38, 55
	s_nop 1
	v_pk_mul_f32 v[122:123], v[44:45], s[0:1]
	v_readlane_b32 s0, v40, 55
	v_add_f32_e32 v122, v129, v122
	v_readlane_b32 s1, v41, 55
	v_add_f32_e32 v129, v122, v123
	s_nop 0
	v_pk_mul_f32 v[122:123], v[46:47], s[0:1]
	v_cmp_lt_f32_e64 s[0:1], |v127|, s36
	v_add_f32_e32 v122, v129, v122
	v_add_f32_e32 v122, v122, v123
	v_mul_f32_e64 v123, |v122|, s31
	v_exp_f32_e32 v123, v123
	v_cndmask_b32_e64 v127, v127, v128, s[0:1]
	v_readlane_b32 s0, v38, 56
	v_cndmask_b32_e32 v128, 0, v99, vcc
	v_add_f32_e32 v123, 1.0, v123
	v_fma_f32 v130, s0, v82, v100
	v_readlane_b32 s0, v39, 56
	v_cmp_gt_f32_e32 vcc, s34, v123
	v_sub_f32_e32 v127, v127, v128
	v_fmac_f32_e32 v130, s0, v83
	v_readlane_b32 s0, v40, 56
	v_cndmask_b32_e64 v128, 0, 32, vcc
	v_ldexp_f32 v123, v123, v128
	v_fmac_f32_e32 v130, s0, v78
	v_readlane_b32 s0, v41, 56
	v_log_f32_e32 v128, v123
	v_sub_f32_e32 v123, v126, v127
	v_fmac_f32_e32 v130, s0, v84
	v_readlane_b32 s0, v38, 57
	v_min_f32_e32 v127, 0, v122
	v_mul_f32_e32 v122, 0x3f317217, v128
	v_fmac_f32_e32 v130, s0, v79
	v_readlane_b32 s0, v39, 57
	v_readlane_b32 s1, v39, 59
	v_fmamk_f32 v126, v123, 0x3d800000, v125
	v_fmac_f32_e32 v130, s0, v80
	v_readlane_b32 s0, v40, 57
	v_fma_f32 v129, v128, s35, -v122
	v_fmac_f32_e32 v129, 0x3377d1cf, v128
	v_fmac_f32_e32 v130, s0, v81
	v_readlane_b32 s0, v41, 57
	v_fmac_f32_e32 v129, 0x3f317217, v128
	s_nop 0
	v_fmac_f32_e32 v130, s0, v85
	v_readlane_b32 s0, v38, 58
	s_nop 1
	v_fmac_f32_e32 v130, s0, v86
	v_readlane_b32 s0, v39, 58
	s_nop 1
	v_fmac_f32_e32 v130, s0, v87
	v_readlane_b32 s0, v40, 58
	s_nop 1
	v_fmac_f32_e32 v130, s0, v88
	v_readlane_b32 s0, v41, 58
	s_nop 1
	v_fmac_f32_e32 v130, s0, v89
	v_readlane_b32 s0, v38, 59
	s_nop 1
	v_pk_mul_f32 v[122:123], v[44:45], s[0:1]
	v_readlane_b32 s0, v40, 59
	v_add_f32_e32 v122, v130, v122
	v_readlane_b32 s1, v41, 59
	v_add_f32_e32 v130, v122, v123
	s_nop 0
	v_pk_mul_f32 v[122:123], v[46:47], s[0:1]
	v_cmp_lt_f32_e64 s[0:1], |v128|, s36
	v_add_f32_e32 v122, v130, v122
	v_add_f32_e32 v122, v122, v123
	v_mul_f32_e64 v123, |v122|, s31
	v_exp_f32_e32 v123, v123
	v_cndmask_b32_e64 v128, v128, v129, s[0:1]
	v_cndmask_b32_e32 v129, 0, v99, vcc
	v_sub_f32_e32 v128, v128, v129
	v_add_f32_e32 v123, 1.0, v123
	v_cmp_gt_f32_e32 vcc, s34, v123
	v_readlane_b32 s0, v38, 60
	v_readlane_b32 s1, v39, 63
	v_cndmask_b32_e64 v129, 0, 32, vcc
	v_ldexp_f32 v123, v123, v129
	v_fma_f32 v129, s0, v82, v100
	v_readlane_b32 s0, v39, 60
	v_log_f32_e32 v123, v123
	v_sub_f32_e32 v127, v127, v128
	v_fmac_f32_e32 v129, s0, v83
	v_readlane_b32 s0, v40, 60
	v_mul_f32_e32 v128, 0x3f317217, v123
	v_fma_f32 v128, v123, s35, -v128
	v_fmac_f32_e32 v129, s0, v78
	v_readlane_b32 s0, v41, 60
	v_fmac_f32_e32 v128, 0x3377d1cf, v123
	v_fmac_f32_e32 v128, 0x3f317217, v123
	v_fmac_f32_e32 v129, s0, v84
	v_readlane_b32 s0, v38, 61
	v_min_f32_e32 v122, 0, v122
	v_fmamk_f32 v127, v127, 0x3d800000, v126
	v_fmac_f32_e32 v129, s0, v79
	v_readlane_b32 s0, v39, 61
	s_nop 1
	v_fmac_f32_e32 v129, s0, v80
	v_readlane_b32 s0, v40, 61
	s_nop 1
	v_fmac_f32_e32 v129, s0, v81
	v_readlane_b32 s0, v41, 61
	s_nop 1
	v_fmac_f32_e32 v129, s0, v85
	v_readlane_b32 s0, v38, 62
	s_nop 1
	v_fmac_f32_e32 v129, s0, v86
	v_readlane_b32 s0, v39, 62
	s_nop 1
	v_fmac_f32_e32 v129, s0, v87
	v_readlane_b32 s0, v40, 62
	s_nop 1
	v_fmac_f32_e32 v129, s0, v88
	v_readlane_b32 s0, v41, 62
	s_nop 1
	v_fmac_f32_e32 v129, s0, v89
	v_readlane_b32 s0, v38, 63
	s_nop 1
	v_pk_mul_f32 v[38:39], v[44:45], s[0:1]
	v_readlane_b32 s0, v40, 63
	v_add_f32_e32 v38, v129, v38
	v_readlane_b32 s1, v41, 63
	v_add_f32_e32 v129, v38, v39
	v_cndmask_b32_e32 v41, 0, v99, vcc
	v_pk_mul_f32 v[38:39], v[46:47], s[0:1]
	v_cmp_lt_f32_e64 s[0:1], |v123|, s36
	v_add_f32_e32 v38, v129, v38
	v_add_f32_e32 v38, v38, v39
	v_mul_f32_e64 v39, |v38|, s31
	v_exp_f32_e32 v39, v39
	v_cndmask_b32_e64 v40, v123, v128, s[0:1]
	v_sub_f32_e32 v40, v40, v41
	v_sub_f32_e32 v40, v122, v40
	v_add_f32_e32 v39, 1.0, v39
	v_cmp_gt_f32_e32 vcc, s34, v39
	v_fmamk_f32 v122, v40, 0x3d800000, v127
	v_min_f32_e32 v38, 0, v38
	v_cndmask_b32_e64 v41, 0, 32, vcc
	v_ldexp_f32 v39, v39, v41
	v_log_f32_e32 v39, v39
	s_nop 0
	v_mul_f32_e32 v40, 0x3f317217, v39
	v_fma_f32 v40, v39, s35, -v40
	v_fmac_f32_e32 v40, 0x3377d1cf, v39
	v_fmac_f32_e32 v40, 0x3f317217, v39
	v_cmp_lt_f32_e64 s[0:1], |v39|, s36
	s_nop 1
	v_cndmask_b32_e64 v39, v39, v40, s[0:1]
	v_cndmask_b32_e32 v40, 0, v99, vcc
	v_sub_f32_e32 v39, v39, v40
	v_sub_f32_e32 v38, v38, v39
	v_fmamk_f32 v123, v38, 0x3d800000, v122
	ds_write_b32 v90, v123
	s_waitcnt lgkmcnt(0)
	s_barrier
	ds_read2st64_b32 v[38:39], v91 offset1:2
	ds_read2st64_b32 v[40:41], v91 offset0:4 offset1:6
	v_cmp_eq_u32_e32 vcc, 1, v76
	s_waitcnt lgkmcnt(1)
	v_add_f32_e32 v128, 0, v38
	v_add_f32_e32 v39, v128, v39
	s_waitcnt lgkmcnt(0)
	v_add_f32_e32 v40, v39, v40
	v_add_f32_e32 v38, v40, v41
	v_cndmask_b32_e32 v41, 0, v128, vcc
	v_cmp_eq_u32_e32 vcc, 2, v76
	s_nop 1
	v_cndmask_b32_e32 v39, v41, v39, vcc
	v_cmp_eq_u32_e32 vcc, 3, v76
	s_nop 1
	v_cndmask_b32_e32 v39, v39, v40, vcc
	v_cmp_eq_u32_e32 vcc, 4, v76
	s_nop 1
	v_cndmask_b32_e32 v39, v39, v38, vcc
	v_sub_f32_e32 v39, v38, v39
	v_sub_f32_e32 v40, v39, v57
	v_sub_f32_e32 v57, v39, v114
	v_mul_f32_e32 v57, 0x3fb8aa3b, v57
	v_exp_f32_e32 v114, v57
	v_sub_f32_e32 v57, v39, v115
	v_mul_f32_e32 v57, 0x3fb8aa3b, v57
	v_exp_f32_e32 v115, v57
	v_sub_f32_e32 v57, v39, v116
	v_mul_f32_e32 v57, 0x3fb8aa3b, v57
	v_exp_f32_e32 v116, v57
	v_sub_f32_e32 v57, v39, v117
	v_mul_f32_e32 v57, 0x3fb8aa3b, v57
	v_sub_f32_e32 v41, v39, v59
	v_exp_f32_e32 v117, v57
	v_sub_f32_e32 v57, v39, v118
	v_mul_f32_e32 v40, 0x3fb8aa3b, v40
	v_mul_f32_e32 v41, 0x3fb8aa3b, v41
	v_mul_f32_e32 v57, 0x3fb8aa3b, v57
	v_exp_f32_e32 v40, v40
	v_exp_f32_e32 v41, v41
	v_exp_f32_e32 v118, v57
	v_sub_f32_e32 v57, v39, v119
	v_mul_f32_e32 v57, 0x3fb8aa3b, v57
	v_exp_f32_e32 v119, v57
	v_sub_f32_e32 v57, v39, v120
	v_mul_f32_e32 v57, 0x3fb8aa3b, v57
	v_pk_mul_f32 v[40:41], v[68:69], v[40:41]
	v_pk_mul_f32 v[68:69], v[70:71], v[114:115]
	v_pk_mul_f32 v[70:71], v[74:75], v[116:117]
	v_exp_f32_e32 v74, v57
	v_sub_f32_e32 v57, v39, v121
	v_mul_f32_e32 v57, 0x3fb8aa3b, v57
	v_exp_f32_e32 v75, v57
	v_sub_f32_e32 v57, v39, v124
	v_mul_f32_e32 v57, 0x3fb8aa3b, v57
	v_exp_f32_e32 v114, v57
	v_sub_f32_e32 v57, v39, v125
	v_mul_f32_e32 v57, 0x3fb8aa3b, v57
	v_exp_f32_e32 v115, v57
	v_sub_f32_e32 v57, v39, v126
	v_mul_f32_e32 v57, 0x3fb8aa3b, v57
	v_exp_f32_e32 v116, v57
	v_sub_f32_e32 v57, v39, v127
	v_mul_f32_e32 v57, 0x3fb8aa3b, v57
	v_exp_f32_e32 v117, v57
	v_sub_f32_e32 v57, v39, v122
	v_sub_f32_e32 v39, v39, v123
	v_mul_f32_e32 v57, 0x3fb8aa3b, v57
	v_mul_f32_e32 v39, 0x3fb8aa3b, v39
	v_pk_mul_f32 v[72:73], v[72:73], v[118:119]
	v_exp_f32_e32 v118, v57
	v_exp_f32_e32 v119, v39
	v_pk_mul_f32 v[74:75], v[60:61], v[74:75]
	v_pk_mul_f32 v[114:115], v[62:63], v[114:115]
	v_pk_mul_f32 v[66:67], v[66:67], v[116:117]
	v_pk_mul_f32 v[116:117], v[64:65], v[118:119]
	v_cvt_pk_bf16_f32 v60, v40, v41
	v_cvt_pk_bf16_f32 v61, v68, v69
	v_cvt_pk_bf16_f32 v62, v70, v71
	v_cvt_pk_bf16_f32 v63, v72, v73
	v_cvt_pk_bf16_f32 v64, v74, v75
	v_cvt_pk_bf16_f32 v65, v114, v115
	v_cvt_pk_bf16_f32 v66, v66, v67
	v_cvt_pk_bf16_f32 v67, v116, v117
	ds_write_b128 v93, v[60:63] offset:2048
	ds_write_b128 v93, v[64:67] offset:2064
	s_and_saveexec_b64 s[0:1], s[2:3]
	s_cbranch_execz .LBB0_1212
	s_lshl_b32 s15, s16, 9
	s_sub_i32 s44, s27, s15
	v_mul_f32_e32 v38, 0x3fb8aa3b, v38
	s_ashr_i32 s45, s44, 31
	s_mul_i32 s33, s16, 0x1800
	v_exp_f32_e32 v38, v38
	s_mul_hi_i32 s15, s16, 0x1800
	s_add_u32 s33, s25, s33
	s_addc_u32 s15, s26, s15
	s_lshl_b64 s[44:45], s[44:45], 2
	s_add_u32 s44, s33, s44
	s_addc_u32 s45, s15, s45
	global_store_dword v94, v38, s[44:45]
	s_branch .LBB0_1212
